# stage-0 merged GEMM final epilogue: gate_pool loads prefetched 11 deep instead of load-wait-store ladder
# speedup vs baseline: 1.0298x; 1.0173x over previous
.LBB0_600:
	ds_read_b128 v[128:131], v188
	ds_read_b128 v[132:135], v188 offset:1024
	ds_read_b128 v[136:139], v188 offset:2048
	ds_read_b128 v[140:143], v188 offset:3072
	s_add_u32 s30, s6, 0xfff80080
	s_addc_u32 s31, s7, -1
	s_cmp_eq_u32 s51, 4
	s_cselect_b32 s35, s25, s31
	s_cselect_b32 s34, s24, s30
	s_cselect_b32 s31, s2, s15
	s_cselect_b32 s30, s3, s13
	v_lshl_add_u64 v[202:203], s[6:7], 0, v[160:161]
	s_add_i32 m0, s29, 0xc000
	ds_read_b128 v[144:147], v189
	ds_read_b128 v[148:151], v189 offset:1024
	ds_read_b128 v[168:171], v189 offset:2048
	ds_read_b128 v[172:175], v189 offset:3072
	ds_read_b128 v[176:179], v189 offset:4096
	ds_read_b128 v[180:183], v189 offset:5120
	ds_read_b128 v[194:197], v189 offset:6144
	ds_read_b128 v[198:201], v189 offset:7168
	global_load_lds_dwordx4 v[202:203], off
	v_lshl_add_u64 v[202:203], s[6:7], 0, v[162:163]
	s_add_i32 m0, s29, 0xe000
	s_nop 0
	global_load_lds_dwordx4 v[202:203], off
	s_waitcnt lgkmcnt(8)
	s_barrier
	s_waitcnt lgkmcnt(0)
	s_setprio 1
	s_waitcnt lgkmcnt(0)
	v_mfma_f32_16x16x32_bf16 v[124:127], v[128:131], v[144:147], v[124:127]
	v_mfma_f32_16x16x32_bf16 v[120:123], v[136:139], v[144:147], v[120:123]
	v_mfma_f32_16x16x32_bf16 v[116:119], v[128:131], v[168:171], v[116:119]
	v_mfma_f32_16x16x32_bf16 v[112:115], v[136:139], v[168:171], v[112:115]
	v_mfma_f32_16x16x32_bf16 v[108:111], v[128:131], v[176:179], v[108:111]
	v_mfma_f32_16x16x32_bf16 v[104:107], v[136:139], v[176:179], v[104:107]
	v_mfma_f32_16x16x32_bf16 v[100:103], v[128:131], v[194:197], v[100:103]
	v_mfma_f32_16x16x32_bf16 v[96:99], v[136:139], v[194:197], v[96:99]
	v_mfma_f32_16x16x32_bf16 v[124:127], v[132:135], v[148:151], v[124:127]
	v_mfma_f32_16x16x32_bf16 v[120:123], v[140:143], v[148:151], v[120:123]
	v_mfma_f32_16x16x32_bf16 v[116:119], v[132:135], v[172:175], v[116:119]
	v_mfma_f32_16x16x32_bf16 v[112:115], v[140:143], v[172:175], v[112:115]
	v_mfma_f32_16x16x32_bf16 v[108:111], v[132:135], v[180:183], v[108:111]
	v_mfma_f32_16x16x32_bf16 v[104:107], v[140:143], v[180:183], v[104:107]
	v_mfma_f32_16x16x32_bf16 v[100:103], v[132:135], v[198:201], v[100:103]
	v_mfma_f32_16x16x32_bf16 v[96:99], v[140:143], v[198:201], v[96:99]
	s_setprio 0
	s_barrier
	s_add_i32 s52, s47, s38
	v_lshl_add_u64 v[218:219], s[30:31], 0, v[156:157]
	s_mov_b32 m0, s52
	ds_read_b128 v[202:205], v190
	ds_read_b128 v[206:209], v190 offset:1024
	ds_read_b128 v[210:213], v190 offset:2048
	ds_read_b128 v[214:217], v190 offset:3072
	global_load_lds_dwordx4 v[218:219], off
	v_lshl_add_u64 v[220:221], s[30:31], 0, v[152:153]
	s_add_i32 m0, s52, 0x2000
	s_nop 0
	global_load_lds_dwordx4 v[220:221], off
	s_barrier
	s_waitcnt lgkmcnt(0)
	s_setprio 1
	s_waitcnt lgkmcnt(0)
	v_mfma_f32_16x16x32_bf16 v[60:63], v[202:205], v[144:147], v[60:63]
	v_mfma_f32_16x16x32_bf16 v[56:59], v[210:213], v[144:147], v[56:59]
	v_mfma_f32_16x16x32_bf16 v[52:55], v[202:205], v[168:171], v[52:55]
	v_mfma_f32_16x16x32_bf16 v[48:51], v[210:213], v[168:171], v[48:51]
	v_mfma_f32_16x16x32_bf16 v[44:47], v[202:205], v[176:179], v[44:47]
	v_mfma_f32_16x16x32_bf16 v[40:43], v[210:213], v[176:179], v[40:43]
	v_mfma_f32_16x16x32_bf16 v[36:39], v[202:205], v[194:197], v[36:39]
	v_mfma_f32_16x16x32_bf16 v[32:35], v[210:213], v[194:197], v[32:35]
	v_mfma_f32_16x16x32_bf16 v[60:63], v[206:209], v[148:151], v[60:63]
	v_mfma_f32_16x16x32_bf16 v[56:59], v[214:217], v[148:151], v[56:59]
	v_mfma_f32_16x16x32_bf16 v[52:55], v[206:209], v[172:175], v[52:55]
	v_mfma_f32_16x16x32_bf16 v[48:51], v[214:217], v[172:175], v[48:51]
	v_mfma_f32_16x16x32_bf16 v[44:47], v[206:209], v[180:183], v[44:47]
	v_mfma_f32_16x16x32_bf16 v[40:43], v[214:217], v[180:183], v[40:43]
	v_mfma_f32_16x16x32_bf16 v[36:39], v[206:209], v[198:201], v[36:39]
	v_mfma_f32_16x16x32_bf16 v[32:35], v[214:217], v[198:201], v[32:35]
	s_setprio 0
	s_mov_b32 m0, s29
	v_lshl_add_u64 v[222:223], s[34:35], 0, v[158:159]
	s_barrier
	ds_read_b128 v[144:147], v189 offset:16384
	ds_read_b128 v[148:151], v189 offset:17408
	ds_read_b128 v[168:171], v189 offset:18432
	ds_read_b128 v[172:175], v189 offset:19456
	ds_read_b128 v[176:179], v189 offset:20480
	ds_read_b128 v[180:183], v189 offset:21504
	ds_read_b128 v[194:197], v189 offset:22528
	ds_read_b128 v[198:201], v189 offset:23552
	global_load_lds_dwordx4 v[222:223], off
	v_lshl_add_u64 v[224:225], s[34:35], 0, v[154:155]
	s_mov_b32 m0, s39
	s_nop 0
	global_load_lds_dwordx4 v[224:225], off
	s_barrier
	s_waitcnt lgkmcnt(0)
	s_setprio 1
	s_waitcnt lgkmcnt(0)
	v_mfma_f32_16x16x32_bf16 v[92:95], v[128:131], v[144:147], v[92:95]
	v_mfma_f32_16x16x32_bf16 v[88:91], v[136:139], v[144:147], v[88:91]
	v_mfma_f32_16x16x32_bf16 v[84:87], v[128:131], v[168:171], v[84:87]
	v_mfma_f32_16x16x32_bf16 v[80:83], v[136:139], v[168:171], v[80:83]
	v_mfma_f32_16x16x32_bf16 v[76:79], v[128:131], v[176:179], v[76:79]
	v_mfma_f32_16x16x32_bf16 v[72:75], v[136:139], v[176:179], v[72:75]
	v_mfma_f32_16x16x32_bf16 v[68:71], v[128:131], v[194:197], v[68:71]
	v_mfma_f32_16x16x32_bf16 v[64:67], v[136:139], v[194:197], v[64:67]
	v_mfma_f32_16x16x32_bf16 v[92:95], v[132:135], v[148:151], v[92:95]
	v_mfma_f32_16x16x32_bf16 v[88:91], v[140:143], v[148:151], v[88:91]
	v_mfma_f32_16x16x32_bf16 v[84:87], v[132:135], v[172:175], v[84:87]
	v_mfma_f32_16x16x32_bf16 v[80:83], v[140:143], v[172:175], v[80:83]
	v_mfma_f32_16x16x32_bf16 v[76:79], v[132:135], v[180:183], v[76:79]
	v_mfma_f32_16x16x32_bf16 v[72:75], v[140:143], v[180:183], v[72:75]
	v_mfma_f32_16x16x32_bf16 v[68:71], v[132:135], v[198:201], v[68:71]
	v_mfma_f32_16x16x32_bf16 v[64:67], v[140:143], v[198:201], v[64:67]
	s_setprio 0
	s_barrier
	s_add_u32 s52, s30, 0x20000
	s_addc_u32 s53, s31, 0
	s_add_i32 s54, s48, s38
	v_lshl_add_u64 v[128:129], s[52:53], 0, v[156:157]
	s_mov_b32 m0, s54
	s_nop 0
	global_load_lds_dwordx4 v[128:129], off
	v_lshl_add_u64 v[128:129], s[52:53], 0, v[152:153]
	s_add_i32 m0, s54, 0x2000
	s_nop 0
	global_load_lds_dwordx4 v[128:129], off
	s_waitcnt vmcnt(6)
	s_barrier
	s_setprio 1
	v_mfma_f32_16x16x32_bf16 v[28:31], v[202:205], v[144:147], v[28:31]
	v_mfma_f32_16x16x32_bf16 v[24:27], v[210:213], v[144:147], v[24:27]
	v_mfma_f32_16x16x32_bf16 v[20:23], v[202:205], v[168:171], v[20:23]
	v_mfma_f32_16x16x32_bf16 v[16:19], v[210:213], v[168:171], v[16:19]
	v_mfma_f32_16x16x32_bf16 v[12:15], v[202:205], v[176:179], v[12:15]
	v_mfma_f32_16x16x32_bf16 v[8:11], v[210:213], v[176:179], v[8:11]
	v_mfma_f32_16x16x32_bf16 v[4:7], v[202:205], v[194:197], v[4:7]
	v_mfma_f32_16x16x32_bf16 v[0:3], v[210:213], v[194:197], v[0:3]
	v_mfma_f32_16x16x32_bf16 v[28:31], v[206:209], v[148:151], v[28:31]
	v_mfma_f32_16x16x32_bf16 v[24:27], v[214:217], v[148:151], v[24:27]
	v_mfma_f32_16x16x32_bf16 v[20:23], v[206:209], v[172:175], v[20:23]
	v_mfma_f32_16x16x32_bf16 v[16:19], v[214:217], v[172:175], v[16:19]
	v_mfma_f32_16x16x32_bf16 v[12:15], v[206:209], v[180:183], v[12:15]
	v_mfma_f32_16x16x32_bf16 v[8:11], v[214:217], v[180:183], v[8:11]
	v_mfma_f32_16x16x32_bf16 v[4:7], v[206:209], v[198:201], v[4:7]
	v_mfma_f32_16x16x32_bf16 v[0:3], v[214:217], v[198:201], v[0:3]
	s_setprio 0
	s_add_i32 s52, 0, 0x18000
	v_add_u32_e32 v140, s52, v186
	s_barrier
	ds_read_b128 v[128:131], v140
	ds_read_b128 v[132:135], v140 offset:1024
	ds_read_b128 v[136:139], v140 offset:2048
	ds_read_b128 v[140:143], v140 offset:3072
	s_add_u32 s34, s34, 0x80000
	s_addc_u32 s35, s35, 0
	s_mov_b32 m0, s40
	v_lshl_add_u64 v[202:203], s[34:35], 0, v[158:159]
	ds_read_b128 v[144:147], v189 offset:32768
	ds_read_b128 v[148:151], v189 offset:33792
	ds_read_b128 v[168:171], v189 offset:34816
	ds_read_b128 v[172:175], v189 offset:35840
	ds_read_b128 v[176:179], v189 offset:36864
	ds_read_b128 v[180:183], v189 offset:37888
	ds_read_b128 v[194:197], v189 offset:38912
	ds_read_b128 v[198:201], v189 offset:39936
	global_load_lds_dwordx4 v[202:203], off
	v_lshl_add_u64 v[202:203], s[34:35], 0, v[154:155]
	s_mov_b32 m0, s41
	s_nop 0
	global_load_lds_dwordx4 v[202:203], off
	s_waitcnt lgkmcnt(8)
	s_barrier
	s_waitcnt lgkmcnt(0)
	s_setprio 1
	s_waitcnt lgkmcnt(0)
	v_mfma_f32_16x16x32_bf16 v[124:127], v[128:131], v[144:147], v[124:127]
	v_mfma_f32_16x16x32_bf16 v[120:123], v[136:139], v[144:147], v[120:123]
	v_mfma_f32_16x16x32_bf16 v[116:119], v[128:131], v[168:171], v[116:119]
	v_mfma_f32_16x16x32_bf16 v[112:115], v[136:139], v[168:171], v[112:115]
	v_mfma_f32_16x16x32_bf16 v[108:111], v[128:131], v[176:179], v[108:111]
	v_mfma_f32_16x16x32_bf16 v[104:107], v[136:139], v[176:179], v[104:107]
	v_mfma_f32_16x16x32_bf16 v[100:103], v[128:131], v[194:197], v[100:103]
	v_mfma_f32_16x16x32_bf16 v[96:99], v[136:139], v[194:197], v[96:99]
	v_mfma_f32_16x16x32_bf16 v[124:127], v[132:135], v[148:151], v[124:127]
	v_mfma_f32_16x16x32_bf16 v[120:123], v[140:143], v[148:151], v[120:123]
	v_mfma_f32_16x16x32_bf16 v[116:119], v[132:135], v[172:175], v[116:119]
	v_mfma_f32_16x16x32_bf16 v[112:115], v[140:143], v[172:175], v[112:115]
	v_mfma_f32_16x16x32_bf16 v[108:111], v[132:135], v[180:183], v[108:111]
	v_mfma_f32_16x16x32_bf16 v[104:107], v[140:143], v[180:183], v[104:107]
	v_mfma_f32_16x16x32_bf16 v[100:103], v[132:135], v[198:201], v[100:103]
	v_mfma_f32_16x16x32_bf16 v[96:99], v[140:143], v[198:201], v[96:99]
	s_setprio 0
	s_barrier
	s_add_i32 s34, 0, 0x1c000
	s_add_i32 s35, s52, s38
	v_add_u32_e32 v191, s34, v186
	v_lshl_add_u64 v[218:219], v[218:219], 0, s[0:1]
	s_mov_b32 m0, s35
	ds_read_b128 v[202:205], v191
	ds_read_b128 v[206:209], v191 offset:1024
	ds_read_b128 v[210:213], v191 offset:2048
	ds_read_b128 v[214:217], v191 offset:3072
	global_load_lds_dwordx4 v[218:219], off
	v_lshl_add_u64 v[218:219], v[220:221], 0, s[0:1]
	s_add_i32 m0, s35, 0x2000
	s_nop 0
	global_load_lds_dwordx4 v[218:219], off
	s_barrier
	s_waitcnt lgkmcnt(0)
	s_setprio 1
	s_waitcnt lgkmcnt(0)
	v_mfma_f32_16x16x32_bf16 v[60:63], v[202:205], v[144:147], v[60:63]
	v_mfma_f32_16x16x32_bf16 v[56:59], v[210:213], v[144:147], v[56:59]
	v_mfma_f32_16x16x32_bf16 v[52:55], v[202:205], v[168:171], v[52:55]
	v_mfma_f32_16x16x32_bf16 v[48:51], v[210:213], v[168:171], v[48:51]
	v_mfma_f32_16x16x32_bf16 v[44:47], v[202:205], v[176:179], v[44:47]
	v_mfma_f32_16x16x32_bf16 v[40:43], v[210:213], v[176:179], v[40:43]
	v_mfma_f32_16x16x32_bf16 v[36:39], v[202:205], v[194:197], v[36:39]
	v_mfma_f32_16x16x32_bf16 v[32:35], v[210:213], v[194:197], v[32:35]
	v_mfma_f32_16x16x32_bf16 v[60:63], v[206:209], v[148:151], v[60:63]
	v_mfma_f32_16x16x32_bf16 v[56:59], v[214:217], v[148:151], v[56:59]
	v_mfma_f32_16x16x32_bf16 v[52:55], v[206:209], v[172:175], v[52:55]
	v_mfma_f32_16x16x32_bf16 v[48:51], v[214:217], v[172:175], v[48:51]
	v_mfma_f32_16x16x32_bf16 v[44:47], v[206:209], v[180:183], v[44:47]
	v_mfma_f32_16x16x32_bf16 v[40:43], v[214:217], v[180:183], v[40:43]
	v_mfma_f32_16x16x32_bf16 v[36:39], v[206:209], v[198:201], v[36:39]
	v_mfma_f32_16x16x32_bf16 v[32:35], v[214:217], v[198:201], v[32:35]
	s_setprio 0
	s_mov_b32 m0, s43
	v_lshl_add_u64 v[218:219], v[222:223], 0, s[0:1]
	s_barrier
	ds_read_b128 v[144:147], v189 offset:49152
	ds_read_b128 v[148:151], v189 offset:50176
	ds_read_b128 v[168:171], v189 offset:51200
	ds_read_b128 v[172:175], v189 offset:52224
	ds_read_b128 v[176:179], v189 offset:53248
	ds_read_b128 v[180:183], v189 offset:54272
	ds_read_b128 v[194:197], v189 offset:55296
	ds_read_b128 v[198:201], v189 offset:56320
	global_load_lds_dwordx4 v[218:219], off
	v_lshl_add_u64 v[218:219], v[224:225], 0, s[0:1]
	s_mov_b32 m0, s44
	s_nop 0
	global_load_lds_dwordx4 v[218:219], off
	s_barrier
; template <class Epi>
; __device__ __forceinline__ void gemm_phase(LAS unsigned char* lds, const GemmD g, const Epi& E) {
;     ...
;         for (int t = 0; t < nt; t += 2) PG8_KITER(t);
;     __device__ __forceinline__ void operator()(const f32x4 (&acc)[2][2][4][2], const Unit& u, int wr, int wc, int fr, int fq) const {
;         const int row0 = u.pm * BM + wr * 64 + fr, col0 = u.pn * BM + wc * 32 + 8 * fq;
; #pragma unroll
;         for (int bj = 0; bj < 2; ++bj) { const int col = col0 + bj * HALF;
;             const f32x4 b0 = *(const f32x4*)(bias + col), b1 = *(const f32x4*)(bias + col + 4), s0 = *(const f32x4*)(scale + col), s1 = *(const f32x4*)(scale + col + 4);
; #pragma unroll
;             for (int ai = 0; ai < 2; ++ai)
; #pragma unroll
;                 for (int m = 0; m < 4; ++m) { const int row = row0 + ai * HALF + m * 16;
;                     const u32x4 z = __builtin_nontemporal_load((const u32x4*)(proj + (size_t)row * NPROJ + C_ZP + col));
;                     f32x4 v0 = (acc[ai][bj][m][0] + b0) * s0, v1 = (acc[ai][bj][m][1] + b1) * s1;
	s_waitcnt lgkmcnt(0)
	s_setprio 1
	s_waitcnt lgkmcnt(0)
	v_mfma_f32_16x16x32_bf16 v[92:95], v[128:131], v[144:147], v[92:95]
	v_mfma_f32_16x16x32_bf16 v[88:91], v[136:139], v[144:147], v[88:91]
	v_mfma_f32_16x16x32_bf16 v[84:87], v[128:131], v[168:171], v[84:87]
	v_mfma_f32_16x16x32_bf16 v[80:83], v[136:139], v[168:171], v[80:83]
	v_mfma_f32_16x16x32_bf16 v[76:79], v[128:131], v[176:179], v[76:79]
	v_mfma_f32_16x16x32_bf16 v[72:75], v[136:139], v[176:179], v[72:75]
	v_mfma_f32_16x16x32_bf16 v[68:71], v[128:131], v[194:197], v[68:71]
	v_mfma_f32_16x16x32_bf16 v[64:67], v[136:139], v[194:197], v[64:67]
	v_mfma_f32_16x16x32_bf16 v[92:95], v[132:135], v[148:151], v[92:95]
	v_mfma_f32_16x16x32_bf16 v[88:91], v[140:143], v[148:151], v[88:91]
	v_mfma_f32_16x16x32_bf16 v[84:87], v[132:135], v[172:175], v[84:87]
	v_mfma_f32_16x16x32_bf16 v[80:83], v[140:143], v[172:175], v[80:83]
	v_mfma_f32_16x16x32_bf16 v[76:79], v[132:135], v[180:183], v[76:79]
	v_mfma_f32_16x16x32_bf16 v[72:75], v[140:143], v[180:183], v[72:75]
	v_mfma_f32_16x16x32_bf16 v[68:71], v[132:135], v[198:201], v[68:71]
	v_mfma_f32_16x16x32_bf16 v[64:67], v[140:143], v[198:201], v[64:67]
	s_setprio 0
	s_barrier
	s_add_u32 s30, s30, 0x20080
	s_addc_u32 s31, s31, 0
	s_add_i32 s34, s34, s38
	v_lshl_add_u64 v[128:129], s[30:31], 0, v[156:157]
	s_mov_b32 m0, s34
	s_nop 0
	global_load_lds_dwordx4 v[128:129], off
	v_lshl_add_u64 v[128:129], s[30:31], 0, v[152:153]
	s_add_i32 m0, s34, 0x2000
	s_nop 0
	global_load_lds_dwordx4 v[128:129], off
	s_waitcnt vmcnt(6)
	s_barrier
	s_setprio 1
	v_mfma_f32_16x16x32_bf16 v[28:31], v[202:205], v[144:147], v[28:31]
	v_mfma_f32_16x16x32_bf16 v[24:27], v[210:213], v[144:147], v[24:27]
	v_mfma_f32_16x16x32_bf16 v[20:23], v[202:205], v[168:171], v[20:23]
	v_mfma_f32_16x16x32_bf16 v[16:19], v[210:213], v[168:171], v[16:19]
	v_mfma_f32_16x16x32_bf16 v[12:15], v[202:205], v[176:179], v[12:15]
	v_mfma_f32_16x16x32_bf16 v[8:11], v[210:213], v[176:179], v[8:11]
	v_mfma_f32_16x16x32_bf16 v[4:7], v[202:205], v[194:197], v[4:7]
	v_mfma_f32_16x16x32_bf16 v[0:3], v[210:213], v[194:197], v[0:3]
	v_mfma_f32_16x16x32_bf16 v[28:31], v[206:209], v[148:151], v[28:31]
	v_mfma_f32_16x16x32_bf16 v[24:27], v[214:217], v[148:151], v[24:27]
	v_mfma_f32_16x16x32_bf16 v[20:23], v[206:209], v[172:175], v[20:23]
	v_mfma_f32_16x16x32_bf16 v[16:19], v[214:217], v[172:175], v[16:19]
	v_mfma_f32_16x16x32_bf16 v[12:15], v[206:209], v[180:183], v[12:15]
	v_mfma_f32_16x16x32_bf16 v[8:11], v[214:217], v[180:183], v[8:11]
	v_mfma_f32_16x16x32_bf16 v[4:7], v[206:209], v[198:201], v[4:7]
	v_mfma_f32_16x16x32_bf16 v[0:3], v[214:217], v[198:201], v[0:3]
	s_setprio 0
	s_add_i32 s51, s51, 2
	s_add_u32 s6, s6, 0x100
	s_addc_u32 s7, s7, 0
	s_add_u32 s13, s13, 0x100
	s_addc_u32 s15, s15, 0
	s_cmp_gt_u32 s51, 5
	s_barrier
	s_cbranch_scc0 .LBB0_600
	v_lshl_add_u32 v176, s28, 8, v185
	v_lshl_or_b32 v148, s50, 8, v187
	v_mov_b64_e32 v[178:179], s[92:93]
	v_ashrrev_i32_e32 v149, 31, v148
	v_readlane_b32 s52, v244, 0
	v_mad_i64_i32 v[138:139], s[2:3], v176, s49, v[178:179]
	v_lshlrev_b64 v[136:137], 2, v[148:149]
	v_readlane_b32 s53, v244, 1
	v_lshl_add_u64 v[150:151], v[138:139], 0, s[8:9]
	v_lshlrev_b64 v[174:175], 1, v[148:149]
	v_lshl_add_u64 v[170:171], s[52:53], 0, v[136:137]
	v_lshl_add_u64 v[138:139], v[150:151], 0, v[174:175]
	global_load_dwordx4 v[128:131], v[170:171], off offset:16
	global_load_dwordx4 v[132:135], v[170:171], off
	v_mov_b32_e32 v254, v138
	v_mov_b32_e32 v255, v139
	global_load_dwordx4 v[144:147], v[138:139], off nt
	v_readlane_b32 s54, v244, 2
	v_readlane_b32 s55, v244, 3
	v_ashrrev_i32_e32 v177, 31, v176
	v_lshlrev_b64 v[168:169], 13, v[176:177]
	v_lshl_add_u64 v[172:173], s[54:55], 0, v[136:137]
	global_load_dwordx4 v[140:143], v[172:173], off
	global_load_dwordx4 v[136:139], v[172:173], off offset:16
	v_readlane_b32 s6, v244, 45
	v_readlane_b32 s7, v244, 46
	v_or_b32_e32 v182, 16, v176
	v_mad_i64_i32 v[194:195], s[2:3], v182, s49, v[178:179]
	v_lshl_add_u64 v[180:181], s[6:7], 0, v[168:169]
	v_lshl_add_u64 v[180:181], v[180:181], 0, s[10:11]
	v_lshl_add_u64 v[196:197], v[180:181], 0, v[174:175]
	v_or_b32_e32 v148, 0x80, v148
	v_ashrrev_i32_e32 v149, 31, v148
	v_lshlrev_b64 v[168:169], 1, v[148:149]
	v_lshl_add_u64 v[148:149], v[150:151], 0, v[168:169]
	global_load_dwordx4 v[148:151], v[148:149], off nt
	s_mov_b32 s60, 0x6a000
	s_mov_b32 s61, 0
	v_lshl_add_u64 v[206:207], v[254:255], 0, s[60:61]
	global_load_dwordx4 v[206:209], v[206:207], off nt
	s_mov_b32 s60, 0xd4000
	s_mov_b32 s61, 0
	v_lshl_add_u64 v[210:211], v[254:255], 0, s[60:61]
	global_load_dwordx4 v[210:213], v[210:211], off nt
	s_mov_b32 s60, 0x13e000
	s_mov_b32 s61, 0
	v_lshl_add_u64 v[214:215], v[254:255], 0, s[60:61]
	global_load_dwordx4 v[214:217], v[214:215], off nt
	s_mov_b32 s60, 0x350000
	s_mov_b32 s61, 0
	v_lshl_add_u64 v[218:219], v[254:255], 0, s[60:61]
	global_load_dwordx4 v[218:221], v[218:219], off nt
	s_mov_b32 s60, 0x3ba000
	s_mov_b32 s61, 0
	v_lshl_add_u64 v[222:223], v[254:255], 0, s[60:61]
	global_load_dwordx4 v[222:225], v[222:223], off nt
	s_mov_b32 s60, 0x424000
	s_mov_b32 s61, 0
	v_lshl_add_u64 v[226:227], v[254:255], 0, s[60:61]
	global_load_dwordx4 v[226:229], v[226:227], off nt
	s_mov_b32 s60, 0x48e000
	s_mov_b32 s61, 0
	v_lshl_add_u64 v[230:231], v[254:255], 0, s[60:61]
	global_load_dwordx4 v[230:233], v[230:231], off nt
	s_and_b64 vcc, exec, s[4:5]
	s_mov_b32 s50, s12
	s_mov_b32 s28, s14
	s_mov_b64 s[30:31], s[26:27]
	s_mov_b64 s[34:35], s[24:25]
	v_readlane_b32 s56, v244, 4
	v_readlane_b32 s57, v244, 5
	v_readlane_b32 s58, v244, 6
	v_readlane_b32 s59, v244, 7
	s_waitcnt vmcnt(8)
; __device__ __forceinline__ float bflo(unsigned w) { return __uint_as_float(w << 16); }
; __device__ __forceinline__ float bfhi(unsigned w) { return __uint_as_float(w & 0xffff0000u); }
; __device__ __forceinline__ unsigned pk2(float lo, float hi) { unsigned r; asm("v_cvt_pk_bf16_f32 %0, %1, %2" : "=v"(r) : "v"(lo), "v"(hi)); return r; }
; __device__ __forceinline__ float siluf_(float x) { return x * __builtin_amdgcn_rcpf(1.0f + __expf(-x)); }
;     __device__ __forceinline__ void operator()(const f32x4 (&acc)[2][2][4][2], const Unit& u, int wr, int wc, int fr, int fq) const {
;     ...
;             for (int ai = 0; ai < 2; ++ai)
; #pragma unroll
;                 for (int m = 0; m < 4; ++m) { const int row = row0 + ai * HALF + m * 16;
;                     const u32x4 z = __builtin_nontemporal_load((const u32x4*)(proj + (size_t)row * NPROJ + C_ZP + col));
;                     f32x4 v0 = (acc[ai][bj][m][0] + b0) * s0, v1 = (acc[ai][bj][m][1] + b1) * s1;
;                     v0[0] *= siluf_(bflo(z.x)); v0[1] *= siluf_(bfhi(z.x)); v0[2] *= siluf_(bflo(z.y)); v0[3] *= siluf_(bfhi(z.y));
;                     v1[0] *= siluf_(bflo(z.z)); v1[1] *= siluf_(bfhi(z.z)); v1[2] *= siluf_(bflo(z.w)); v1[3] *= siluf_(bfhi(z.w));
;                     u32x4 w; w.x = pk2(v0[0], v0[1]); w.y = pk2(v0[2], v0[3]); w.z = pk2(v1[0], v1[1]); w.w = pk2(v1[2], v1[3]);
;                     *(u32x4*)(a2 + (size_t)row * 4096 + 2048 + col) = w; } }
	v_pk_add_f32 v[122:123], v[122:123], v[130:131]
	v_pk_add_f32 v[124:125], v[124:125], v[132:133]
	v_lshlrev_b32_e32 v177, 16, v144
	v_and_b32_e32 v144, 0xffff0000, v144
	v_lshlrev_b32_e32 v183, 16, v145
	v_and_b32_e32 v145, 0xffff0000, v145
	v_lshlrev_b32_e32 v191, 16, v146
	v_and_b32_e32 v146, 0xffff0000, v146
	v_lshlrev_b32_e32 v193, 16, v147
	v_and_b32_e32 v147, 0xffff0000, v147
	v_mul_f32_e32 v198, 0xbfb8aa3b, v177
	v_mul_f32_e32 v199, 0xbfb8aa3b, v144
	v_mul_f32_e32 v200, 0xbfb8aa3b, v183
	v_mul_f32_e32 v201, 0xbfb8aa3b, v145
	v_mul_f32_e32 v202, 0xbfb8aa3b, v191
	v_mul_f32_e32 v203, 0xbfb8aa3b, v146
	v_mul_f32_e32 v205, 0xbfb8aa3b, v147
	v_exp_f32_e32 v198, v198
	v_exp_f32_e32 v199, v199
	v_mul_f32_e32 v204, 0xbfb8aa3b, v193
	v_exp_f32_e32 v200, v200
	v_exp_f32_e32 v201, v201
	v_exp_f32_e32 v202, v202
	v_exp_f32_e32 v203, v203
	v_exp_f32_e32 v205, v205
	v_exp_f32_e32 v204, v204
	v_add_f32_e32 v198, 1.0, v198
	v_add_f32_e32 v199, 1.0, v199
	v_add_f32_e32 v200, 1.0, v200
	v_add_f32_e32 v201, 1.0, v201
	v_add_f32_e32 v202, 1.0, v202
	v_add_f32_e32 v203, 1.0, v203
	v_add_f32_e32 v205, 1.0, v205
	v_rcp_f32_e32 v198, v198
	v_rcp_f32_e32 v199, v199
	v_add_f32_e32 v204, 1.0, v204
	v_rcp_f32_e32 v200, v200
	v_rcp_f32_e32 v201, v201
	v_rcp_f32_e32 v202, v202
	v_rcp_f32_e32 v203, v203
	v_rcp_f32_e32 v205, v205
	v_rcp_f32_e32 v204, v204
	v_pk_add_f32 v[126:127], v[126:127], v[134:135]
	v_pk_add_f32 v[120:121], v[120:121], v[128:129]
	v_pk_mul_f32 v[124:125], v[124:125], v[140:141]
	v_mul_f32_e32 v177, v198, v177
	v_mul_f32_e32 v144, v199, v144
	v_pk_mul_f32 v[126:127], v[126:127], v[142:143]
	v_pk_mul_f32 v[122:123], v[122:123], v[138:139]
	v_pk_mul_f32 v[120:121], v[120:121], v[136:137]
	v_mul_f32_e32 v183, v200, v183
	v_mul_f32_e32 v145, v201, v145
	v_mul_f32_e32 v191, v202, v191
	v_mul_f32_e32 v146, v203, v146
	v_mul_f32_e32 v147, v205, v147
	v_mul_f32_e32 v124, v124, v177
	v_mul_f32_e32 v125, v125, v144
	v_mul_f32_e32 v193, v204, v193
	v_mul_f32_e32 v126, v126, v183
	v_mul_f32_e32 v127, v127, v145
	v_mul_f32_e32 v144, v120, v191
	v_mul_f32_e32 v145, v121, v146
	v_mul_f32_e32 v123, v123, v147
	v_cvt_pk_bf16_f32 v120, v124, v125
	v_cvt_pk_bf16_f32 v121, v126, v127
	v_lshl_add_u64 v[124:125], v[194:195], 0, s[8:9]
	v_mul_f32_e32 v146, v122, v193
	v_cvt_pk_bf16_f32 v122, v144, v145
	v_cvt_pk_bf16_f32 v123, v146, v123
	global_store_dwordx4 v[196:197], v[120:123], off
	v_ashrrev_i32_e32 v183, 31, v182
	v_or_b32_e32 v126, 32, v176
	v_lshl_add_u64 v[120:121], v[124:125], 0, v[174:175]
	v_lshlrev_b64 v[122:123], 13, v[182:183]
	v_lshl_add_u64 v[122:123], s[6:7], 0, v[122:123]
	v_pk_add_f32 v[114:115], v[114:115], v[130:131]
	v_mad_i64_i32 v[120:121], s[2:3], v126, s49, v[178:179]
	v_lshl_add_u64 v[122:123], v[122:123], 0, s[10:11]
	v_pk_add_f32 v[118:119], v[118:119], v[134:135]
	v_pk_add_f32 v[116:117], v[116:117], v[132:133]
	v_pk_add_f32 v[112:113], v[112:113], v[128:129]
	v_pk_mul_f32 v[114:115], v[114:115], v[138:139]
	v_lshl_add_u64 v[120:121], v[120:121], 0, s[8:9]
	v_lshl_add_u64 v[194:195], v[122:123], 0, v[174:175]
	v_pk_mul_f32 v[118:119], v[118:119], v[142:143]
	v_pk_mul_f32 v[116:117], v[116:117], v[140:141]
	v_pk_mul_f32 v[112:113], v[112:113], v[136:137]
	v_lshl_add_u64 v[182:183], v[120:121], 0, v[174:175]
	v_pk_add_f32 v[106:107], v[106:107], v[130:131]
	v_pk_add_f32 v[110:111], v[110:111], v[134:135]
	v_pk_add_f32 v[108:109], v[108:109], v[132:133]
	v_pk_add_f32 v[104:105], v[104:105], v[128:129]
	v_pk_mul_f32 v[106:107], v[106:107], v[138:139]
	v_pk_mul_f32 v[110:111], v[110:111], v[142:143]
	v_pk_mul_f32 v[108:109], v[108:109], v[140:141]
	v_pk_mul_f32 v[104:105], v[104:105], v[136:137]
	v_pk_add_f32 v[98:99], v[98:99], v[130:131]
	v_pk_add_f32 v[102:103], v[102:103], v[134:135]
	v_pk_add_f32 v[100:101], v[100:101], v[132:133]
	v_pk_add_f32 v[96:97], v[96:97], v[128:129]
	v_pk_mul_f32 v[98:99], v[98:99], v[138:139]
	v_pk_mul_f32 v[102:103], v[102:103], v[142:143]
	v_pk_mul_f32 v[100:101], v[100:101], v[140:141]
	v_pk_mul_f32 v[96:97], v[96:97], v[136:137]
	v_pk_add_f32 v[90:91], v[90:91], v[130:131]
	v_pk_add_f32 v[94:95], v[94:95], v[134:135]
	v_pk_add_f32 v[92:93], v[92:93], v[132:133]
	v_pk_add_f32 v[88:89], v[88:89], v[128:129]
	v_pk_mul_f32 v[90:91], v[90:91], v[138:139]
	v_pk_mul_f32 v[94:95], v[94:95], v[142:143]
	v_pk_mul_f32 v[92:93], v[92:93], v[140:141]
	v_pk_mul_f32 v[88:89], v[88:89], v[136:137]
	v_pk_add_f32 v[82:83], v[82:83], v[130:131]
	v_pk_add_f32 v[86:87], v[86:87], v[134:135]
	v_pk_add_f32 v[84:85], v[84:85], v[132:133]
	v_pk_add_f32 v[80:81], v[80:81], v[128:129]
	v_pk_mul_f32 v[82:83], v[82:83], v[138:139]
	v_pk_mul_f32 v[86:87], v[86:87], v[142:143]
	v_pk_mul_f32 v[84:85], v[84:85], v[140:141]
	v_pk_mul_f32 v[80:81], v[80:81], v[136:137]
	v_pk_add_f32 v[74:75], v[74:75], v[130:131]
	v_pk_add_f32 v[78:79], v[78:79], v[134:135]
	v_pk_add_f32 v[76:77], v[76:77], v[132:133]
	v_pk_add_f32 v[72:73], v[72:73], v[128:129]
	v_pk_mul_f32 v[74:75], v[74:75], v[138:139]
	v_pk_mul_f32 v[78:79], v[78:79], v[142:143]
	v_pk_mul_f32 v[76:77], v[76:77], v[140:141]
	v_pk_mul_f32 v[72:73], v[72:73], v[136:137]
	v_pk_add_f32 v[66:67], v[66:67], v[130:131]
	v_pk_add_f32 v[70:71], v[70:71], v[134:135]
	v_pk_add_f32 v[68:69], v[68:69], v[132:133]
	v_pk_add_f32 v[64:65], v[64:65], v[128:129]
	v_pk_mul_f32 v[66:67], v[66:67], v[138:139]
	v_pk_mul_f32 v[70:71], v[70:71], v[142:143]
	v_pk_mul_f32 v[68:69], v[68:69], v[140:141]
	v_pk_mul_f32 v[64:65], v[64:65], v[136:137]
	s_waitcnt vmcnt(7)
; __device__ __forceinline__ float bflo(unsigned w) { return __uint_as_float(w << 16); }
; __device__ __forceinline__ float bfhi(unsigned w) { return __uint_as_float(w & 0xffff0000u); }
; __device__ __forceinline__ unsigned pk2(float lo, float hi) { unsigned r; asm("v_cvt_pk_bf16_f32 %0, %1, %2" : "=v"(r) : "v"(lo), "v"(hi)); return r; }
; __device__ __forceinline__ float siluf_(float x) { return x * __builtin_amdgcn_rcpf(1.0f + __expf(-x)); }
;     __device__ __forceinline__ void operator()(const f32x4 (&acc)[2][2][4][2], const Unit& u, int wr, int wc, int fr, int fq) const {
;     ...
;             for (int ai = 0; ai < 2; ++ai)
; #pragma unroll
;                 for (int m = 0; m < 4; ++m) { const int row = row0 + ai * HALF + m * 16;
;                     const u32x4 z = __builtin_nontemporal_load((const u32x4*)(proj + (size_t)row * NPROJ + C_ZP + col));
;                     f32x4 v0 = (acc[ai][bj][m][0] + b0) * s0, v1 = (acc[ai][bj][m][1] + b1) * s1;
;                     v0[0] *= siluf_(bflo(z.x)); v0[1] *= siluf_(bfhi(z.x)); v0[2] *= siluf_(bflo(z.y)); v0[3] *= siluf_(bfhi(z.y));
;                     v1[0] *= siluf_(bflo(z.z)); v1[1] *= siluf_(bfhi(z.z)); v1[2] *= siluf_(bflo(z.w)); v1[3] *= siluf_(bfhi(z.w));
;                     u32x4 w; w.x = pk2(v0[0], v0[1]); w.y = pk2(v0[2], v0[3]); w.z = pk2(v1[0], v1[1]); w.w = pk2(v1[2], v1[3]);
;                     *(u32x4*)(a2 + (size_t)row * 4096 + 2048 + col) = w; } }
	v_mov_b32_e32 v144, v206
	v_mov_b32_e32 v145, v207
	v_mov_b32_e32 v146, v208
	v_mov_b32_e32 v147, v209
	s_mov_b32 s60, 0x6a100
	s_mov_b32 s61, 0
	v_lshl_add_u64 v[206:207], v[254:255], 0, s[60:61]
	global_load_dwordx4 v[206:209], v[206:207], off nt
	v_lshlrev_b32_e32 v193, 16, v147
	v_and_b32_e32 v147, 0xffff0000, v147
	v_lshlrev_b32_e32 v127, 16, v144
	v_and_b32_e32 v144, 0xffff0000, v144
	v_lshlrev_b32_e32 v177, 16, v145
	v_and_b32_e32 v145, 0xffff0000, v145
	v_lshlrev_b32_e32 v191, 16, v146
	v_and_b32_e32 v146, 0xffff0000, v146
	v_mul_f32_e32 v203, 0xbfb8aa3b, v147
	v_mul_f32_e32 v196, 0xbfb8aa3b, v127
	v_mul_f32_e32 v197, 0xbfb8aa3b, v144
	v_mul_f32_e32 v198, 0xbfb8aa3b, v177
	v_mul_f32_e32 v199, 0xbfb8aa3b, v145
	v_mul_f32_e32 v200, 0xbfb8aa3b, v191
	v_mul_f32_e32 v201, 0xbfb8aa3b, v146
	v_mul_f32_e32 v202, 0xbfb8aa3b, v193
	v_exp_f32_e32 v203, v203
	v_exp_f32_e32 v196, v196
	v_exp_f32_e32 v197, v197
	v_exp_f32_e32 v198, v198
	v_exp_f32_e32 v199, v199
	v_exp_f32_e32 v200, v200
	v_exp_f32_e32 v201, v201
	v_exp_f32_e32 v202, v202
	v_add_f32_e32 v203, 1.0, v203
	v_add_f32_e32 v196, 1.0, v196
	v_add_f32_e32 v197, 1.0, v197
	v_add_f32_e32 v198, 1.0, v198
	v_add_f32_e32 v199, 1.0, v199
	v_add_f32_e32 v200, 1.0, v200
	v_add_f32_e32 v201, 1.0, v201
	v_add_f32_e32 v202, 1.0, v202
	v_rcp_f32_e32 v203, v203
	v_rcp_f32_e32 v196, v196
	v_rcp_f32_e32 v197, v197
	v_rcp_f32_e32 v198, v198
	v_rcp_f32_e32 v199, v199
	v_rcp_f32_e32 v200, v200
	v_rcp_f32_e32 v201, v201
	v_rcp_f32_e32 v202, v202
	v_mul_f32_e32 v147, v203, v147
	v_mul_f32_e32 v127, v196, v127
	v_mul_f32_e32 v144, v197, v144
	v_mul_f32_e32 v177, v198, v177
	v_mul_f32_e32 v145, v199, v145
	v_mul_f32_e32 v191, v200, v191
	v_mul_f32_e32 v146, v201, v146
	v_mul_f32_e32 v193, v202, v193
	v_mul_f32_e32 v115, v115, v147
	v_mul_f32_e32 v116, v116, v127
	v_mul_f32_e32 v117, v117, v144
	v_mul_f32_e32 v118, v118, v177
	v_mul_f32_e32 v119, v119, v145
	v_mul_f32_e32 v127, v112, v191
	v_mul_f32_e32 v144, v113, v146
	v_mul_f32_e32 v145, v114, v193
	v_cvt_pk_bf16_f32 v112, v116, v117
	v_cvt_pk_bf16_f32 v113, v118, v119
	v_cvt_pk_bf16_f32 v114, v127, v144
	v_cvt_pk_bf16_f32 v115, v145, v115
	global_store_dwordx4 v[194:195], v[112:115], off
	v_ashrrev_i32_e32 v127, 31, v126
	v_lshlrev_b64 v[114:115], 13, v[126:127]
	v_or_b32_e32 v144, 48, v176
	v_lshl_add_u64 v[114:115], s[6:7], 0, v[114:115]
	v_mad_i64_i32 v[112:113], s[2:3], v144, s49, v[178:179]
	v_lshl_add_u64 v[114:115], v[114:115], 0, s[10:11]
	v_lshl_add_u64 v[112:113], v[112:113], 0, s[8:9]
	v_lshl_add_u64 v[146:147], v[114:115], 0, v[174:175]
	v_lshl_add_u64 v[126:127], v[112:113], 0, v[174:175]
	s_waitcnt vmcnt(8)
	v_mov_b32_e32 v116, v210
	v_mov_b32_e32 v117, v211
	v_mov_b32_e32 v118, v212
	v_mov_b32_e32 v119, v213
	s_mov_b32 s60, 0xd4100
	s_mov_b32 s61, 0
	v_lshl_add_u64 v[210:211], v[254:255], 0, s[60:61]
	global_load_dwordx4 v[210:213], v[210:211], off nt
	v_lshlrev_b32_e32 v183, 16, v119
	v_and_b32_e32 v119, 0xffff0000, v119
	v_lshlrev_b32_e32 v145, 16, v116
	v_and_b32_e32 v116, 0xffff0000, v116
	v_lshlrev_b32_e32 v177, 16, v117
	v_and_b32_e32 v117, 0xffff0000, v117
	v_lshlrev_b32_e32 v182, 16, v118
	v_and_b32_e32 v118, 0xffff0000, v118
	v_mul_f32_e32 v199, 0xbfb8aa3b, v119
	v_mul_f32_e32 v191, 0xbfb8aa3b, v145
	v_mul_f32_e32 v193, 0xbfb8aa3b, v116
	v_mul_f32_e32 v194, 0xbfb8aa3b, v177
	v_mul_f32_e32 v195, 0xbfb8aa3b, v117
	v_mul_f32_e32 v196, 0xbfb8aa3b, v182
	v_mul_f32_e32 v197, 0xbfb8aa3b, v118
	v_mul_f32_e32 v198, 0xbfb8aa3b, v183
	v_exp_f32_e32 v199, v199
	v_exp_f32_e32 v191, v191
	v_exp_f32_e32 v193, v193
	v_exp_f32_e32 v194, v194
	v_exp_f32_e32 v195, v195
	v_exp_f32_e32 v196, v196
	v_exp_f32_e32 v197, v197
	v_exp_f32_e32 v198, v198
	v_add_f32_e32 v199, 1.0, v199
	v_add_f32_e32 v191, 1.0, v191
	v_add_f32_e32 v193, 1.0, v193
	v_add_f32_e32 v194, 1.0, v194
	v_add_f32_e32 v195, 1.0, v195
	v_add_f32_e32 v196, 1.0, v196
	v_add_f32_e32 v197, 1.0, v197
	v_add_f32_e32 v198, 1.0, v198
	v_rcp_f32_e32 v199, v199
	v_rcp_f32_e32 v191, v191
	v_rcp_f32_e32 v193, v193
	v_rcp_f32_e32 v194, v194
	v_rcp_f32_e32 v195, v195
	v_rcp_f32_e32 v196, v196
	v_rcp_f32_e32 v197, v197
	v_rcp_f32_e32 v198, v198
	v_mul_f32_e32 v119, v199, v119
	v_mul_f32_e32 v145, v191, v145
	v_mul_f32_e32 v116, v193, v116
	v_mul_f32_e32 v177, v194, v177
	v_mul_f32_e32 v117, v195, v117
	v_mul_f32_e32 v182, v196, v182
	v_mul_f32_e32 v118, v197, v118
	v_mul_f32_e32 v183, v198, v183
	v_mul_f32_e32 v107, v107, v119
	v_mul_f32_e32 v108, v108, v145
	v_mul_f32_e32 v109, v109, v116
	v_mul_f32_e32 v110, v110, v177
	v_mul_f32_e32 v111, v111, v117
	v_mul_f32_e32 v116, v104, v182
	v_mul_f32_e32 v117, v105, v118
	v_mul_f32_e32 v118, v106, v183
	v_cvt_pk_bf16_f32 v104, v108, v109
	v_cvt_pk_bf16_f32 v105, v110, v111
	v_cvt_pk_bf16_f32 v106, v116, v117
	v_cvt_pk_bf16_f32 v107, v118, v107
	global_store_dwordx4 v[146:147], v[104:107], off
	v_ashrrev_i32_e32 v145, 31, v144
	v_lshlrev_b64 v[106:107], 13, v[144:145]
	v_add_u32_e32 v116, 0x80, v176
	v_lshl_add_u64 v[106:107], s[6:7], 0, v[106:107]
	v_mad_i64_i32 v[104:105], s[2:3], v116, s49, v[178:179]
	v_lshl_add_u64 v[106:107], v[106:107], 0, s[10:11]
	v_lshl_add_u64 v[104:105], v[104:105], 0, s[8:9]
	v_lshl_add_u64 v[126:127], v[106:107], 0, v[174:175]
	v_lshl_add_u64 v[118:119], v[104:105], 0, v[174:175]
	s_waitcnt vmcnt(9)
; __device__ __forceinline__ float bflo(unsigned w) { return __uint_as_float(w << 16); }
; __device__ __forceinline__ float bfhi(unsigned w) { return __uint_as_float(w & 0xffff0000u); }
; __device__ __forceinline__ unsigned pk2(float lo, float hi) { unsigned r; asm("v_cvt_pk_bf16_f32 %0, %1, %2" : "=v"(r) : "v"(lo), "v"(hi)); return r; }
; __device__ __forceinline__ float siluf_(float x) { return x * __builtin_amdgcn_rcpf(1.0f + __expf(-x)); }
;     __device__ __forceinline__ void operator()(const f32x4 (&acc)[2][2][4][2], const Unit& u, int wr, int wc, int fr, int fq) const {
;     ...
;             for (int ai = 0; ai < 2; ++ai)
; #pragma unroll
;                 for (int m = 0; m < 4; ++m) { const int row = row0 + ai * HALF + m * 16;
;                     const u32x4 z = __builtin_nontemporal_load((const u32x4*)(proj + (size_t)row * NPROJ + C_ZP + col));
;                     f32x4 v0 = (acc[ai][bj][m][0] + b0) * s0, v1 = (acc[ai][bj][m][1] + b1) * s1;
;                     v0[0] *= siluf_(bflo(z.x)); v0[1] *= siluf_(bfhi(z.x)); v0[2] *= siluf_(bflo(z.y)); v0[3] *= siluf_(bfhi(z.y));
;                     v1[0] *= siluf_(bflo(z.z)); v1[1] *= siluf_(bfhi(z.z)); v1[2] *= siluf_(bflo(z.w)); v1[3] *= siluf_(bfhi(z.w));
;                     u32x4 w; w.x = pk2(v0[0], v0[1]); w.y = pk2(v0[2], v0[3]); w.z = pk2(v1[0], v1[1]); w.w = pk2(v1[2], v1[3]);
;                     *(u32x4*)(a2 + (size_t)row * 4096 + 2048 + col) = w; } }
	v_mov_b32_e32 v108, v214
	v_mov_b32_e32 v109, v215
	v_mov_b32_e32 v110, v216
	v_mov_b32_e32 v111, v217
	s_mov_b32 s60, 0x13e100
	s_mov_b32 s61, 0
	v_lshl_add_u64 v[214:215], v[254:255], 0, s[60:61]
	global_load_dwordx4 v[214:217], v[214:215], off nt
	v_lshlrev_b32_e32 v146, 16, v111
	v_and_b32_e32 v111, 0xffff0000, v111
	v_lshlrev_b32_e32 v117, 16, v108
	v_and_b32_e32 v108, 0xffff0000, v108
	v_lshlrev_b32_e32 v144, 16, v109
	v_and_b32_e32 v109, 0xffff0000, v109
	v_lshlrev_b32_e32 v145, 16, v110
	v_and_b32_e32 v110, 0xffff0000, v110
	v_mul_f32_e32 v195, 0xbfb8aa3b, v111
	v_mul_f32_e32 v147, 0xbfb8aa3b, v117
	v_mul_f32_e32 v177, 0xbfb8aa3b, v108
	v_mul_f32_e32 v182, 0xbfb8aa3b, v144
	v_mul_f32_e32 v183, 0xbfb8aa3b, v109
	v_mul_f32_e32 v191, 0xbfb8aa3b, v145
	v_mul_f32_e32 v193, 0xbfb8aa3b, v110
	v_mul_f32_e32 v194, 0xbfb8aa3b, v146
	v_exp_f32_e32 v195, v195
	v_exp_f32_e32 v147, v147
	v_exp_f32_e32 v177, v177
	v_exp_f32_e32 v182, v182
	v_exp_f32_e32 v183, v183
	v_exp_f32_e32 v191, v191
	v_exp_f32_e32 v193, v193
	v_exp_f32_e32 v194, v194
	v_add_f32_e32 v195, 1.0, v195
	v_add_f32_e32 v147, 1.0, v147
	v_add_f32_e32 v177, 1.0, v177
	v_add_f32_e32 v182, 1.0, v182
	v_add_f32_e32 v183, 1.0, v183
	v_add_f32_e32 v191, 1.0, v191
	v_add_f32_e32 v193, 1.0, v193
	v_add_f32_e32 v194, 1.0, v194
	v_rcp_f32_e32 v195, v195
	v_rcp_f32_e32 v147, v147
	v_rcp_f32_e32 v177, v177
	v_rcp_f32_e32 v182, v182
	v_rcp_f32_e32 v183, v183
	v_rcp_f32_e32 v191, v191
	v_rcp_f32_e32 v193, v193
	v_rcp_f32_e32 v194, v194
	v_mul_f32_e32 v111, v195, v111
	v_mul_f32_e32 v117, v147, v117
	v_mul_f32_e32 v108, v177, v108
	v_mul_f32_e32 v144, v182, v144
	v_mul_f32_e32 v109, v183, v109
	v_mul_f32_e32 v145, v191, v145
	v_mul_f32_e32 v110, v193, v110
	v_mul_f32_e32 v146, v194, v146
	v_mul_f32_e32 v99, v99, v111
	v_mul_f32_e32 v100, v100, v117
	v_mul_f32_e32 v101, v101, v108
	v_mul_f32_e32 v102, v102, v144
	v_mul_f32_e32 v103, v103, v109
	v_mul_f32_e32 v108, v96, v145
	v_mul_f32_e32 v109, v97, v110
	v_mul_f32_e32 v110, v98, v146
	v_cvt_pk_bf16_f32 v96, v100, v101
	v_cvt_pk_bf16_f32 v97, v102, v103
	v_cvt_pk_bf16_f32 v98, v108, v109
	v_cvt_pk_bf16_f32 v99, v110, v99
	global_store_dwordx4 v[126:127], v[96:99], off
	v_ashrrev_i32_e32 v117, 31, v116
	v_lshlrev_b64 v[98:99], 13, v[116:117]
	v_add_u32_e32 v108, 0x90, v176
	v_lshl_add_u64 v[98:99], s[6:7], 0, v[98:99]
	v_mad_i64_i32 v[96:97], s[2:3], v108, s49, v[178:179]
	v_lshl_add_u64 v[98:99], v[98:99], 0, s[10:11]
	v_lshl_add_u64 v[96:97], v[96:97], 0, s[8:9]
	v_lshl_add_u64 v[116:117], v[98:99], 0, v[174:175]
	v_lshl_add_u64 v[110:111], v[96:97], 0, v[174:175]
	s_waitcnt vmcnt(10)
	v_mov_b32_e32 v100, v218
	v_mov_b32_e32 v101, v219
	v_mov_b32_e32 v102, v220
	v_mov_b32_e32 v103, v221
	s_mov_b32 s60, 0x350100
	s_mov_b32 s61, 0
	v_lshl_add_u64 v[218:219], v[254:255], 0, s[60:61]
	global_load_dwordx4 v[218:221], v[218:219], off nt
	v_lshlrev_b32_e32 v126, 16, v103
	v_and_b32_e32 v103, 0xffff0000, v103
	v_lshlrev_b32_e32 v109, 16, v100
	v_and_b32_e32 v100, 0xffff0000, v100
	v_lshlrev_b32_e32 v118, 16, v101
	v_and_b32_e32 v101, 0xffff0000, v101
	v_lshlrev_b32_e32 v119, 16, v102
	v_and_b32_e32 v102, 0xffff0000, v102
	v_mul_f32_e32 v183, 0xbfb8aa3b, v103
	v_mul_f32_e32 v127, 0xbfb8aa3b, v109
	v_mul_f32_e32 v144, 0xbfb8aa3b, v100
	v_mul_f32_e32 v145, 0xbfb8aa3b, v118
	v_mul_f32_e32 v146, 0xbfb8aa3b, v101
	v_mul_f32_e32 v147, 0xbfb8aa3b, v119
	v_mul_f32_e32 v177, 0xbfb8aa3b, v102
	v_mul_f32_e32 v182, 0xbfb8aa3b, v126
	v_exp_f32_e32 v183, v183
	v_exp_f32_e32 v127, v127
	v_exp_f32_e32 v144, v144
	v_exp_f32_e32 v145, v145
	v_exp_f32_e32 v146, v146
	v_exp_f32_e32 v147, v147
	v_exp_f32_e32 v177, v177
	v_exp_f32_e32 v182, v182
	v_add_f32_e32 v183, 1.0, v183
	v_add_f32_e32 v127, 1.0, v127
	v_add_f32_e32 v144, 1.0, v144
	v_add_f32_e32 v145, 1.0, v145
	v_add_f32_e32 v146, 1.0, v146
	v_add_f32_e32 v147, 1.0, v147
	v_add_f32_e32 v177, 1.0, v177
	v_add_f32_e32 v182, 1.0, v182
	v_rcp_f32_e32 v183, v183
	v_rcp_f32_e32 v127, v127
	v_rcp_f32_e32 v144, v144
	v_rcp_f32_e32 v145, v145
	v_rcp_f32_e32 v146, v146
	v_rcp_f32_e32 v147, v147
	v_rcp_f32_e32 v177, v177
	v_rcp_f32_e32 v182, v182
	v_mul_f32_e32 v103, v183, v103
	v_mul_f32_e32 v109, v127, v109
	v_mul_f32_e32 v100, v144, v100
	v_mul_f32_e32 v118, v145, v118
	v_mul_f32_e32 v101, v146, v101
	v_mul_f32_e32 v119, v147, v119
	v_mul_f32_e32 v102, v177, v102
	v_mul_f32_e32 v126, v182, v126
	v_mul_f32_e32 v91, v91, v103
	v_mul_f32_e32 v92, v92, v109
	v_mul_f32_e32 v93, v93, v100
	v_mul_f32_e32 v94, v94, v118
	v_mul_f32_e32 v95, v95, v101
	v_mul_f32_e32 v100, v88, v119
	v_mul_f32_e32 v101, v89, v102
	v_mul_f32_e32 v102, v90, v126
	v_cvt_pk_bf16_f32 v88, v92, v93
	v_cvt_pk_bf16_f32 v89, v94, v95
	v_cvt_pk_bf16_f32 v90, v100, v101
	v_cvt_pk_bf16_f32 v91, v102, v91
	global_store_dwordx4 v[116:117], v[88:91], off
	v_ashrrev_i32_e32 v109, 31, v108
	v_lshlrev_b64 v[90:91], 13, v[108:109]
	v_add_u32_e32 v100, 0xa0, v176
	v_lshl_add_u64 v[90:91], s[6:7], 0, v[90:91]
	v_mad_i64_i32 v[88:89], s[2:3], v100, s49, v[178:179]
	v_lshl_add_u64 v[90:91], v[90:91], 0, s[10:11]
	v_lshl_add_u64 v[88:89], v[88:89], 0, s[8:9]
	v_lshl_add_u64 v[108:109], v[90:91], 0, v[174:175]
	v_lshl_add_u64 v[102:103], v[88:89], 0, v[174:175]
	s_waitcnt vmcnt(11)
; __device__ __forceinline__ float bflo(unsigned w) { return __uint_as_float(w << 16); }
; __device__ __forceinline__ float bfhi(unsigned w) { return __uint_as_float(w & 0xffff0000u); }
; __device__ __forceinline__ unsigned pk2(float lo, float hi) { unsigned r; asm("v_cvt_pk_bf16_f32 %0, %1, %2" : "=v"(r) : "v"(lo), "v"(hi)); return r; }
; __device__ __forceinline__ float siluf_(float x) { return x * __builtin_amdgcn_rcpf(1.0f + __expf(-x)); }
;     __device__ __forceinline__ void operator()(const f32x4 (&acc)[2][2][4][2], const Unit& u, int wr, int wc, int fr, int fq) const {
;     ...
;             for (int ai = 0; ai < 2; ++ai)
; #pragma unroll
;                 for (int m = 0; m < 4; ++m) { const int row = row0 + ai * HALF + m * 16;
;                     const u32x4 z = __builtin_nontemporal_load((const u32x4*)(proj + (size_t)row * NPROJ + C_ZP + col));
;                     f32x4 v0 = (acc[ai][bj][m][0] + b0) * s0, v1 = (acc[ai][bj][m][1] + b1) * s1;
;                     v0[0] *= siluf_(bflo(z.x)); v0[1] *= siluf_(bfhi(z.x)); v0[2] *= siluf_(bflo(z.y)); v0[3] *= siluf_(bfhi(z.y));
;                     v1[0] *= siluf_(bflo(z.z)); v1[1] *= siluf_(bfhi(z.z)); v1[2] *= siluf_(bflo(z.w)); v1[3] *= siluf_(bfhi(z.w));
;                     u32x4 w; w.x = pk2(v0[0], v0[1]); w.y = pk2(v0[2], v0[3]); w.z = pk2(v1[0], v1[1]); w.w = pk2(v1[2], v1[3]);
;                     *(u32x4*)(a2 + (size_t)row * 4096 + 2048 + col) = w; } }
	v_mov_b32_e32 v92, v222
	v_mov_b32_e32 v93, v223
	v_mov_b32_e32 v94, v224
	v_mov_b32_e32 v95, v225
	s_mov_b32 s60, 0x3ba100
	s_mov_b32 s61, 0
	v_lshl_add_u64 v[222:223], v[254:255], 0, s[60:61]
	global_load_dwordx4 v[222:225], v[222:223], off nt
	v_lshlrev_b32_e32 v116, 16, v95
	v_and_b32_e32 v95, 0xffff0000, v95
	v_lshlrev_b32_e32 v101, 16, v92
	v_and_b32_e32 v92, 0xffff0000, v92
	v_lshlrev_b32_e32 v110, 16, v93
	v_and_b32_e32 v93, 0xffff0000, v93
	v_lshlrev_b32_e32 v111, 16, v94
	v_and_b32_e32 v94, 0xffff0000, v94
	v_mul_f32_e32 v146, 0xbfb8aa3b, v95
	v_mul_f32_e32 v117, 0xbfb8aa3b, v101
	v_mul_f32_e32 v118, 0xbfb8aa3b, v92
	v_mul_f32_e32 v119, 0xbfb8aa3b, v110
	v_mul_f32_e32 v126, 0xbfb8aa3b, v93
	v_mul_f32_e32 v127, 0xbfb8aa3b, v111
	v_mul_f32_e32 v144, 0xbfb8aa3b, v94
	v_mul_f32_e32 v145, 0xbfb8aa3b, v116
	v_exp_f32_e32 v146, v146
	v_exp_f32_e32 v117, v117
	v_exp_f32_e32 v118, v118
	v_exp_f32_e32 v119, v119
	v_exp_f32_e32 v126, v126
	v_exp_f32_e32 v127, v127
	v_exp_f32_e32 v144, v144
	v_exp_f32_e32 v145, v145
	v_add_f32_e32 v146, 1.0, v146
	v_add_f32_e32 v117, 1.0, v117
	v_add_f32_e32 v118, 1.0, v118
	v_add_f32_e32 v119, 1.0, v119
	v_add_f32_e32 v126, 1.0, v126
	v_add_f32_e32 v127, 1.0, v127
	v_add_f32_e32 v144, 1.0, v144
	v_add_f32_e32 v145, 1.0, v145
	v_rcp_f32_e32 v146, v146
	v_rcp_f32_e32 v117, v117
	v_rcp_f32_e32 v118, v118
	v_rcp_f32_e32 v119, v119
	v_rcp_f32_e32 v126, v126
	v_rcp_f32_e32 v127, v127
	v_rcp_f32_e32 v144, v144
	v_rcp_f32_e32 v145, v145
	v_mul_f32_e32 v95, v146, v95
	v_mul_f32_e32 v101, v117, v101
	v_mul_f32_e32 v92, v118, v92
	v_mul_f32_e32 v110, v119, v110
	v_mul_f32_e32 v93, v126, v93
	v_mul_f32_e32 v111, v127, v111
	v_mul_f32_e32 v94, v144, v94
	v_mul_f32_e32 v116, v145, v116
	v_mul_f32_e32 v83, v83, v95
	v_mul_f32_e32 v84, v84, v101
	v_mul_f32_e32 v85, v85, v92
	v_mul_f32_e32 v86, v86, v110
	v_mul_f32_e32 v87, v87, v93
	v_mul_f32_e32 v92, v80, v111
	v_mul_f32_e32 v93, v81, v94
	v_mul_f32_e32 v94, v82, v116
	v_cvt_pk_bf16_f32 v80, v84, v85
	v_cvt_pk_bf16_f32 v81, v86, v87
	v_cvt_pk_bf16_f32 v82, v92, v93
	v_cvt_pk_bf16_f32 v83, v94, v83
	global_store_dwordx4 v[108:109], v[80:83], off
	v_ashrrev_i32_e32 v101, 31, v100
	v_lshlrev_b64 v[84:85], 13, v[100:101]
	v_add_u32_e32 v80, 0xb0, v176
	v_lshl_add_u64 v[84:85], s[6:7], 0, v[84:85]
	v_mad_i64_i32 v[82:83], s[2:3], v80, s49, v[178:179]
	v_lshl_add_u64 v[84:85], v[84:85], 0, s[10:11]
	v_lshl_add_u64 v[82:83], v[82:83], 0, s[8:9]
	v_lshl_add_u64 v[100:101], v[84:85], 0, v[174:175]
	v_lshl_add_u64 v[86:87], v[82:83], 0, v[174:175]
	s_waitcnt vmcnt(12)
	v_mov_b32_e32 v92, v226
	v_mov_b32_e32 v93, v227
	v_mov_b32_e32 v94, v228
	v_mov_b32_e32 v95, v229
	s_mov_b32 s60, 0x424100
	s_mov_b32 s61, 0
	v_lshl_add_u64 v[226:227], v[254:255], 0, s[60:61]
	global_load_dwordx4 v[226:229], v[226:227], off nt
	v_lshlrev_b32_e32 v108, 16, v95
	v_and_b32_e32 v95, 0xffff0000, v95
	v_lshlrev_b32_e32 v81, 16, v92
	v_and_b32_e32 v92, 0xffff0000, v92
	v_lshlrev_b32_e32 v102, 16, v93
	v_and_b32_e32 v93, 0xffff0000, v93
	v_lshlrev_b32_e32 v103, 16, v94
	v_and_b32_e32 v94, 0xffff0000, v94
	v_mul_f32_e32 v126, 0xbfb8aa3b, v95
	v_mul_f32_e32 v109, 0xbfb8aa3b, v81
	v_mul_f32_e32 v110, 0xbfb8aa3b, v92
	v_mul_f32_e32 v111, 0xbfb8aa3b, v102
	v_mul_f32_e32 v116, 0xbfb8aa3b, v93
	v_mul_f32_e32 v117, 0xbfb8aa3b, v103
	v_mul_f32_e32 v118, 0xbfb8aa3b, v94
	v_mul_f32_e32 v119, 0xbfb8aa3b, v108
	v_exp_f32_e32 v126, v126
	v_exp_f32_e32 v109, v109
	v_exp_f32_e32 v110, v110
	v_exp_f32_e32 v111, v111
	v_exp_f32_e32 v116, v116
	v_exp_f32_e32 v117, v117
	v_exp_f32_e32 v118, v118
	v_exp_f32_e32 v119, v119
	v_add_f32_e32 v126, 1.0, v126
	v_add_f32_e32 v109, 1.0, v109
	v_add_f32_e32 v110, 1.0, v110
	v_add_f32_e32 v111, 1.0, v111
	v_add_f32_e32 v116, 1.0, v116
	v_add_f32_e32 v117, 1.0, v117
	v_add_f32_e32 v118, 1.0, v118
	v_add_f32_e32 v119, 1.0, v119
	v_rcp_f32_e32 v126, v126
	v_rcp_f32_e32 v109, v109
	v_rcp_f32_e32 v110, v110
	v_rcp_f32_e32 v111, v111
	v_rcp_f32_e32 v116, v116
	v_rcp_f32_e32 v117, v117
	v_rcp_f32_e32 v118, v118
	v_rcp_f32_e32 v119, v119
	v_mul_f32_e32 v95, v126, v95
	v_mul_f32_e32 v81, v109, v81
	v_mul_f32_e32 v92, v110, v92
	v_mul_f32_e32 v102, v111, v102
	v_mul_f32_e32 v93, v116, v93
	v_mul_f32_e32 v103, v117, v103
	v_mul_f32_e32 v94, v118, v94
	v_mul_f32_e32 v108, v119, v108
	v_mul_f32_e32 v75, v75, v95
	v_mul_f32_e32 v76, v76, v81
	v_mul_f32_e32 v77, v77, v92
	v_mul_f32_e32 v78, v78, v102
	v_mul_f32_e32 v79, v79, v93
	v_mul_f32_e32 v81, v72, v103
	v_mul_f32_e32 v92, v73, v94
	v_mul_f32_e32 v93, v74, v108
	v_cvt_pk_bf16_f32 v72, v76, v77
	v_cvt_pk_bf16_f32 v73, v78, v79
	v_cvt_pk_bf16_f32 v74, v81, v92
	v_cvt_pk_bf16_f32 v75, v93, v75
	global_store_dwordx4 v[100:101], v[72:75], off
	v_ashrrev_i32_e32 v81, 31, v80
	v_lshlrev_b64 v[76:77], 13, v[80:81]
	v_lshl_add_u64 v[76:77], s[6:7], 0, v[76:77]
	v_lshl_add_u64 v[80:81], v[76:77], 0, s[10:11]
	v_lshl_add_u64 v[76:77], v[80:81], 0, v[174:175]
	v_and_b32_e32 v109, 0xffff0000, v151
	v_lshlrev_b32_e32 v108, 16, v151
	s_waitcnt vmcnt(13)
; __device__ __forceinline__ float bflo(unsigned w) { return __uint_as_float(w << 16); }
; __device__ __forceinline__ float bfhi(unsigned w) { return __uint_as_float(w & 0xffff0000u); }
; __device__ __forceinline__ unsigned pk2(float lo, float hi) { unsigned r; asm("v_cvt_pk_bf16_f32 %0, %1, %2" : "=v"(r) : "v"(lo), "v"(hi)); return r; }
; __device__ __forceinline__ float siluf_(float x) { return x * __builtin_amdgcn_rcpf(1.0f + __expf(-x)); }
;     __device__ __forceinline__ void operator()(const f32x4 (&acc)[2][2][4][2], const Unit& u, int wr, int wc, int fr, int fq) const {
;     ...
;         for (int bj = 0; bj < 2; ++bj) { const int col = col0 + bj * HALF;
;             const f32x4 b0 = *(const f32x4*)(bias + col), b1 = *(const f32x4*)(bias + col + 4), s0 = *(const f32x4*)(scale + col), s1 = *(const f32x4*)(scale + col + 4);
; #pragma unroll
;             for (int ai = 0; ai < 2; ++ai)
; #pragma unroll
;                 for (int m = 0; m < 4; ++m) { const int row = row0 + ai * HALF + m * 16;
;                     const u32x4 z = __builtin_nontemporal_load((const u32x4*)(proj + (size_t)row * NPROJ + C_ZP + col));
;                     f32x4 v0 = (acc[ai][bj][m][0] + b0) * s0, v1 = (acc[ai][bj][m][1] + b1) * s1;
;                     v0[0] *= siluf_(bflo(z.x)); v0[1] *= siluf_(bfhi(z.x)); v0[2] *= siluf_(bflo(z.y)); v0[3] *= siluf_(bfhi(z.y));
;                     v1[0] *= siluf_(bflo(z.z)); v1[1] *= siluf_(bfhi(z.z)); v1[2] *= siluf_(bflo(z.w)); v1[3] *= siluf_(bfhi(z.w));
;                     u32x4 w; w.x = pk2(v0[0], v0[1]); w.y = pk2(v0[2], v0[3]); w.z = pk2(v1[0], v1[1]); w.w = pk2(v1[2], v1[3]);
;                     *(u32x4*)(a2 + (size_t)row * 4096 + 2048 + col) = w; } }
	v_mov_b32_e32 v72, v230
	v_mov_b32_e32 v73, v231
	v_mov_b32_e32 v74, v232
	v_mov_b32_e32 v75, v233
	s_mov_b32 s60, 0x48e100
	s_mov_b32 s61, 0
	v_lshl_add_u64 v[230:231], v[254:255], 0, s[60:61]
	global_load_dwordx4 v[230:233], v[230:231], off nt
	v_lshlrev_b32_e32 v87, 16, v75
	v_and_b32_e32 v75, 0xffff0000, v75
	v_lshlrev_b32_e32 v78, 16, v72
	v_and_b32_e32 v72, 0xffff0000, v72
	v_lshlrev_b32_e32 v79, 16, v73
	v_and_b32_e32 v73, 0xffff0000, v73
	v_lshlrev_b32_e32 v86, 16, v74
	v_and_b32_e32 v74, 0xffff0000, v74
	v_mul_f32_e32 v103, 0xbfb8aa3b, v75
	v_mul_f32_e32 v92, 0xbfb8aa3b, v78
	v_mul_f32_e32 v93, 0xbfb8aa3b, v72
	v_mul_f32_e32 v94, 0xbfb8aa3b, v79
	v_mul_f32_e32 v95, 0xbfb8aa3b, v73
	v_mul_f32_e32 v100, 0xbfb8aa3b, v86
	v_mul_f32_e32 v101, 0xbfb8aa3b, v74
	v_mul_f32_e32 v102, 0xbfb8aa3b, v87
	v_exp_f32_e32 v103, v103
	v_exp_f32_e32 v92, v92
	v_exp_f32_e32 v93, v93
	v_exp_f32_e32 v94, v94
	v_exp_f32_e32 v95, v95
	v_exp_f32_e32 v100, v100
	v_exp_f32_e32 v101, v101
	v_exp_f32_e32 v102, v102
	v_add_f32_e32 v103, 1.0, v103
	v_add_f32_e32 v92, 1.0, v92
	v_add_f32_e32 v93, 1.0, v93
	v_add_f32_e32 v94, 1.0, v94
	v_add_f32_e32 v95, 1.0, v95
	v_add_f32_e32 v100, 1.0, v100
	v_add_f32_e32 v101, 1.0, v101
	v_add_f32_e32 v102, 1.0, v102
	v_rcp_f32_e32 v103, v103
	v_rcp_f32_e32 v92, v92
	v_rcp_f32_e32 v93, v93
	v_rcp_f32_e32 v94, v94
	v_rcp_f32_e32 v95, v95
	v_rcp_f32_e32 v100, v100
	v_rcp_f32_e32 v101, v101
	v_rcp_f32_e32 v102, v102
	v_mul_f32_e32 v75, v103, v75
	v_mul_f32_e32 v78, v92, v78
	v_mul_f32_e32 v72, v93, v72
	v_mul_f32_e32 v79, v94, v79
	v_mul_f32_e32 v73, v95, v73
	v_mul_f32_e32 v86, v100, v86
	v_mul_f32_e32 v74, v101, v74
	v_mul_f32_e32 v87, v102, v87
	v_mul_f32_e32 v67, v67, v75
	v_mul_f32_e32 v68, v68, v78
	v_mul_f32_e32 v69, v69, v72
	v_mul_f32_e32 v70, v70, v79
	v_mul_f32_e32 v71, v71, v73
	v_mul_f32_e32 v72, v64, v86
	v_mul_f32_e32 v73, v65, v74
	v_mul_f32_e32 v74, v66, v87
	v_cvt_pk_bf16_f32 v64, v68, v69
	v_cvt_pk_bf16_f32 v65, v70, v71
	v_cvt_pk_bf16_f32 v66, v72, v73
	v_cvt_pk_bf16_f32 v67, v74, v67
	global_store_dwordx4 v[76:77], v[64:67], off
	global_load_dwordx4 v[76:79], v[170:171], off offset:512
	s_nop 0
	global_load_dwordx4 v[72:75], v[170:171], off offset:528
	global_load_dwordx4 v[68:71], v[172:173], off offset:512
	global_load_dwordx4 v[64:67], v[172:173], off offset:528
	v_lshl_add_u64 v[86:87], v[124:125], 0, v[168:169]
	v_lshlrev_b32_e32 v94, 16, v148
	v_and_b32_e32 v95, 0xffff0000, v148
	v_lshlrev_b32_e32 v100, 16, v149
	v_and_b32_e32 v101, 0xffff0000, v149
	v_lshlrev_b32_e32 v102, 16, v150
	v_and_b32_e32 v103, 0xffff0000, v150
	v_mul_f32_e32 v125, 0xbfb8aa3b, v109
	v_mul_f32_e32 v110, 0xbfb8aa3b, v94
	v_mul_f32_e32 v111, 0xbfb8aa3b, v95
	v_mul_f32_e32 v116, 0xbfb8aa3b, v100
	v_mul_f32_e32 v117, 0xbfb8aa3b, v101
	v_mul_f32_e32 v118, 0xbfb8aa3b, v102
	v_mul_f32_e32 v119, 0xbfb8aa3b, v103
	v_mul_f32_e32 v124, 0xbfb8aa3b, v108
	v_exp_f32_e32 v125, v125
	v_exp_f32_e32 v110, v110
	v_exp_f32_e32 v111, v111
	v_exp_f32_e32 v116, v116
	v_exp_f32_e32 v117, v117
	v_exp_f32_e32 v118, v118
	v_exp_f32_e32 v119, v119
	v_exp_f32_e32 v124, v124
	v_add_f32_e32 v125, 1.0, v125
	v_add_f32_e32 v110, 1.0, v110
	v_add_f32_e32 v111, 1.0, v111
	v_add_f32_e32 v116, 1.0, v116
	v_add_f32_e32 v117, 1.0, v117
	v_add_f32_e32 v118, 1.0, v118
	v_add_f32_e32 v119, 1.0, v119
	v_add_f32_e32 v124, 1.0, v124
	v_rcp_f32_e32 v125, v125
	v_rcp_f32_e32 v110, v110
	v_rcp_f32_e32 v111, v111
	v_rcp_f32_e32 v116, v116
	v_rcp_f32_e32 v117, v117
	v_rcp_f32_e32 v118, v118
	v_rcp_f32_e32 v119, v119
	v_rcp_f32_e32 v124, v124
	v_mul_f32_e32 v109, v125, v109
	v_lshl_add_u64 v[92:93], v[180:181], 0, v[168:169]
	v_mul_f32_e32 v94, v110, v94
	v_mul_f32_e32 v95, v111, v95
	v_mul_f32_e32 v100, v116, v100
	v_mul_f32_e32 v101, v117, v101
	v_mul_f32_e32 v102, v118, v102
	v_mul_f32_e32 v103, v119, v103
	v_mul_f32_e32 v108, v124, v108
	s_waitcnt vmcnt(0)
	v_pk_add_f32 v[62:63], v[62:63], v[78:79]
	v_pk_add_f32 v[58:59], v[58:59], v[74:75]
	v_pk_add_f32 v[60:61], v[60:61], v[76:77]
	v_pk_add_f32 v[56:57], v[56:57], v[72:73]
	v_pk_mul_f32 v[58:59], v[58:59], v[66:67]
	v_pk_mul_f32 v[62:63], v[62:63], v[70:71]
	v_pk_mul_f32 v[60:61], v[60:61], v[68:69]
	v_pk_mul_f32 v[56:57], v[56:57], v[64:65]
	v_mul_f32_e32 v59, v59, v109
	v_mul_f32_e32 v60, v60, v94
	v_mul_f32_e32 v61, v61, v95
	v_mul_f32_e32 v62, v62, v100
	v_mul_f32_e32 v63, v63, v101
	v_mul_f32_e32 v94, v56, v102
	v_mul_f32_e32 v95, v57, v103
	v_mul_f32_e32 v100, v58, v108
	v_cvt_pk_bf16_f32 v56, v60, v61
	v_cvt_pk_bf16_f32 v57, v62, v63
	v_cvt_pk_bf16_f32 v58, v94, v95
	v_cvt_pk_bf16_f32 v59, v100, v59
	global_store_dwordx4 v[92:93], v[56:59], off
	v_pk_add_f32 v[50:51], v[50:51], v[74:75]
	v_pk_add_f32 v[54:55], v[54:55], v[78:79]
	v_pk_add_f32 v[52:53], v[52:53], v[76:77]
	v_pk_add_f32 v[48:49], v[48:49], v[72:73]
	v_pk_mul_f32 v[50:51], v[50:51], v[66:67]
	v_lshl_add_u64 v[62:63], v[122:123], 0, v[168:169]
	v_pk_mul_f32 v[54:55], v[54:55], v[70:71]
	v_pk_mul_f32 v[52:53], v[52:53], v[68:69]
	v_pk_mul_f32 v[48:49], v[48:49], v[64:65]
	v_lshl_add_u64 v[60:61], v[120:121], 0, v[168:169]
	v_pk_add_f32 v[42:43], v[42:43], v[74:75]
	v_pk_add_f32 v[46:47], v[46:47], v[78:79]
	v_pk_add_f32 v[44:45], v[44:45], v[76:77]
	v_pk_add_f32 v[40:41], v[40:41], v[72:73]
	v_pk_mul_f32 v[42:43], v[42:43], v[66:67]
	v_pk_mul_f32 v[46:47], v[46:47], v[70:71]
	v_pk_mul_f32 v[44:45], v[44:45], v[68:69]
	v_pk_mul_f32 v[40:41], v[40:41], v[64:65]
	v_pk_add_f32 v[34:35], v[34:35], v[74:75]
	v_pk_add_f32 v[38:39], v[38:39], v[78:79]
	v_pk_add_f32 v[36:37], v[36:37], v[76:77]
	v_pk_add_f32 v[32:33], v[32:33], v[72:73]
; __device__ __forceinline__ float bflo(unsigned w) { return __uint_as_float(w << 16); }
; __device__ __forceinline__ float bfhi(unsigned w) { return __uint_as_float(w & 0xffff0000u); }
; __device__ __forceinline__ unsigned pk2(float lo, float hi) { unsigned r; asm("v_cvt_pk_bf16_f32 %0, %1, %2" : "=v"(r) : "v"(lo), "v"(hi)); return r; }
; __device__ __forceinline__ float siluf_(float x) { return x * __builtin_amdgcn_rcpf(1.0f + __expf(-x)); }
;     __device__ __forceinline__ void operator()(const f32x4 (&acc)[2][2][4][2], const Unit& u, int wr, int wc, int fr, int fq) const {
;     ...
;             for (int ai = 0; ai < 2; ++ai)
; #pragma unroll
;                 for (int m = 0; m < 4; ++m) { const int row = row0 + ai * HALF + m * 16;
;                     const u32x4 z = __builtin_nontemporal_load((const u32x4*)(proj + (size_t)row * NPROJ + C_ZP + col));
;                     f32x4 v0 = (acc[ai][bj][m][0] + b0) * s0, v1 = (acc[ai][bj][m][1] + b1) * s1;
;                     v0[0] *= siluf_(bflo(z.x)); v0[1] *= siluf_(bfhi(z.x)); v0[2] *= siluf_(bflo(z.y)); v0[3] *= siluf_(bfhi(z.y));
;                     v1[0] *= siluf_(bflo(z.z)); v1[1] *= siluf_(bfhi(z.z)); v1[2] *= siluf_(bflo(z.w)); v1[3] *= siluf_(bfhi(z.w));
;                     u32x4 w; w.x = pk2(v0[0], v0[1]); w.y = pk2(v0[2], v0[3]); w.z = pk2(v1[0], v1[1]); w.w = pk2(v1[2], v1[3]);
;                     *(u32x4*)(a2 + (size_t)row * 4096 + 2048 + col) = w; } }
	v_pk_mul_f32 v[34:35], v[34:35], v[66:67]
	v_pk_mul_f32 v[38:39], v[38:39], v[70:71]
	v_pk_mul_f32 v[36:37], v[36:37], v[68:69]
	v_pk_mul_f32 v[32:33], v[32:33], v[64:65]
	v_pk_add_f32 v[26:27], v[26:27], v[74:75]
	v_pk_add_f32 v[30:31], v[30:31], v[78:79]
	v_pk_add_f32 v[28:29], v[28:29], v[76:77]
	v_pk_add_f32 v[24:25], v[24:25], v[72:73]
	v_pk_mul_f32 v[26:27], v[26:27], v[66:67]
	v_pk_mul_f32 v[30:31], v[30:31], v[70:71]
	v_pk_mul_f32 v[28:29], v[28:29], v[68:69]
	v_pk_mul_f32 v[24:25], v[24:25], v[64:65]
	v_pk_add_f32 v[18:19], v[18:19], v[74:75]
	v_pk_add_f32 v[22:23], v[22:23], v[78:79]
	v_pk_add_f32 v[20:21], v[20:21], v[76:77]
	v_pk_add_f32 v[16:17], v[16:17], v[72:73]
	v_pk_mul_f32 v[18:19], v[18:19], v[66:67]
	v_pk_mul_f32 v[22:23], v[22:23], v[70:71]
	v_pk_mul_f32 v[20:21], v[20:21], v[68:69]
	v_pk_mul_f32 v[16:17], v[16:17], v[64:65]
	v_pk_add_f32 v[10:11], v[10:11], v[74:75]
	v_pk_add_f32 v[14:15], v[14:15], v[78:79]
	v_pk_add_f32 v[12:13], v[12:13], v[76:77]
	v_pk_add_f32 v[8:9], v[8:9], v[72:73]
	v_pk_mul_f32 v[10:11], v[10:11], v[66:67]
	v_pk_mul_f32 v[14:15], v[14:15], v[70:71]
	v_pk_mul_f32 v[12:13], v[12:13], v[68:69]
	v_pk_mul_f32 v[8:9], v[8:9], v[64:65]
	v_pk_add_f32 v[2:3], v[2:3], v[74:75]
	v_pk_add_f32 v[6:7], v[6:7], v[78:79]
	v_pk_add_f32 v[4:5], v[4:5], v[76:77]
	v_pk_add_f32 v[0:1], v[0:1], v[72:73]
	v_pk_mul_f32 v[2:3], v[2:3], v[66:67]
	v_pk_mul_f32 v[6:7], v[6:7], v[70:71]
	v_pk_mul_f32 v[4:5], v[4:5], v[68:69]
	v_pk_mul_f32 v[0:1], v[0:1], v[64:65]
	s_waitcnt vmcnt(18)
	v_mov_b32_e32 v56, v206
	v_mov_b32_e32 v57, v207
	v_mov_b32_e32 v58, v208
	v_mov_b32_e32 v59, v209
	v_lshlrev_b32_e32 v93, 16, v59
	v_and_b32_e32 v59, 0xffff0000, v59
	v_lshlrev_b32_e32 v86, 16, v56
	v_and_b32_e32 v56, 0xffff0000, v56
	v_lshlrev_b32_e32 v87, 16, v57
	v_and_b32_e32 v57, 0xffff0000, v57
	v_lshlrev_b32_e32 v92, 16, v58
	v_and_b32_e32 v58, 0xffff0000, v58
	v_mul_f32_e32 v109, 0xbfb8aa3b, v59
	v_mul_f32_e32 v94, 0xbfb8aa3b, v86
	v_mul_f32_e32 v95, 0xbfb8aa3b, v56
	v_mul_f32_e32 v100, 0xbfb8aa3b, v87
	v_mul_f32_e32 v101, 0xbfb8aa3b, v57
	v_mul_f32_e32 v102, 0xbfb8aa3b, v92
	v_mul_f32_e32 v103, 0xbfb8aa3b, v58
	v_mul_f32_e32 v108, 0xbfb8aa3b, v93
	v_exp_f32_e32 v109, v109
	v_exp_f32_e32 v94, v94
	v_exp_f32_e32 v95, v95
	v_exp_f32_e32 v100, v100
	v_exp_f32_e32 v101, v101
	v_exp_f32_e32 v102, v102
	v_exp_f32_e32 v103, v103
	v_exp_f32_e32 v108, v108
	v_add_f32_e32 v109, 1.0, v109
	v_add_f32_e32 v94, 1.0, v94
	v_add_f32_e32 v95, 1.0, v95
	v_add_f32_e32 v100, 1.0, v100
	v_add_f32_e32 v101, 1.0, v101
	v_add_f32_e32 v102, 1.0, v102
	v_add_f32_e32 v103, 1.0, v103
	v_add_f32_e32 v108, 1.0, v108
	v_rcp_f32_e32 v109, v109
	v_rcp_f32_e32 v94, v94
	v_rcp_f32_e32 v95, v95
	v_rcp_f32_e32 v100, v100
	v_rcp_f32_e32 v101, v101
	v_rcp_f32_e32 v102, v102
	v_rcp_f32_e32 v103, v103
	v_rcp_f32_e32 v108, v108
	v_mul_f32_e32 v59, v109, v59
	v_mul_f32_e32 v86, v94, v86
	v_mul_f32_e32 v56, v95, v56
	v_mul_f32_e32 v87, v100, v87
	v_mul_f32_e32 v57, v101, v57
	v_mul_f32_e32 v92, v102, v92
	v_mul_f32_e32 v58, v103, v58
	v_mul_f32_e32 v93, v108, v93
	v_mul_f32_e32 v51, v51, v59
	v_mul_f32_e32 v52, v52, v86
	v_mul_f32_e32 v53, v53, v56
	v_mul_f32_e32 v54, v54, v87
	v_mul_f32_e32 v55, v55, v57
	v_mul_f32_e32 v56, v48, v92
	v_mul_f32_e32 v57, v49, v58
	v_mul_f32_e32 v58, v50, v93
	v_cvt_pk_bf16_f32 v48, v52, v53
	v_cvt_pk_bf16_f32 v49, v54, v55
	v_cvt_pk_bf16_f32 v50, v56, v57
	v_cvt_pk_bf16_f32 v51, v58, v51
	global_store_dwordx4 v[62:63], v[48:51], off
	v_lshl_add_u64 v[54:55], v[114:115], 0, v[168:169]
	v_lshl_add_u64 v[52:53], v[112:113], 0, v[168:169]
	s_waitcnt vmcnt(17)
	v_mov_b32_e32 v48, v210
	v_mov_b32_e32 v49, v211
	v_mov_b32_e32 v50, v212
	v_mov_b32_e32 v51, v213
	v_lshlrev_b32_e32 v59, 16, v51
	v_and_b32_e32 v51, 0xffff0000, v51
	v_lshlrev_b32_e32 v56, 16, v48
	v_and_b32_e32 v48, 0xffff0000, v48
	v_lshlrev_b32_e32 v57, 16, v49
	v_and_b32_e32 v49, 0xffff0000, v49
	v_lshlrev_b32_e32 v58, 16, v50
	v_and_b32_e32 v50, 0xffff0000, v50
	v_mul_f32_e32 v93, 0xbfb8aa3b, v51
	v_mul_f32_e32 v60, 0xbfb8aa3b, v56
	v_mul_f32_e32 v61, 0xbfb8aa3b, v48
	v_mul_f32_e32 v62, 0xbfb8aa3b, v57
	v_mul_f32_e32 v63, 0xbfb8aa3b, v49
	v_mul_f32_e32 v86, 0xbfb8aa3b, v58
	v_mul_f32_e32 v87, 0xbfb8aa3b, v50
	v_mul_f32_e32 v92, 0xbfb8aa3b, v59
	v_exp_f32_e32 v93, v93
	v_exp_f32_e32 v60, v60
	v_exp_f32_e32 v61, v61
	v_exp_f32_e32 v62, v62
	v_exp_f32_e32 v63, v63
	v_exp_f32_e32 v86, v86
	v_exp_f32_e32 v87, v87
	v_exp_f32_e32 v92, v92
	v_add_f32_e32 v93, 1.0, v93
	v_add_f32_e32 v60, 1.0, v60
	v_add_f32_e32 v61, 1.0, v61
	v_add_f32_e32 v62, 1.0, v62
	v_add_f32_e32 v63, 1.0, v63
	v_add_f32_e32 v86, 1.0, v86
	v_add_f32_e32 v87, 1.0, v87
	v_add_f32_e32 v92, 1.0, v92
	v_rcp_f32_e32 v93, v93
	v_rcp_f32_e32 v60, v60
	v_rcp_f32_e32 v61, v61
	v_rcp_f32_e32 v62, v62
	v_rcp_f32_e32 v63, v63
	v_rcp_f32_e32 v86, v86
	v_rcp_f32_e32 v87, v87
	v_rcp_f32_e32 v92, v92
	v_mul_f32_e32 v51, v93, v51
	v_mul_f32_e32 v56, v60, v56
	v_mul_f32_e32 v48, v61, v48
	v_mul_f32_e32 v57, v62, v57
	v_mul_f32_e32 v49, v63, v49
	v_mul_f32_e32 v58, v86, v58
	v_mul_f32_e32 v50, v87, v50
	v_mul_f32_e32 v59, v92, v59
	v_mul_f32_e32 v43, v43, v51
	v_mul_f32_e32 v44, v44, v56
	v_mul_f32_e32 v45, v45, v48
	v_mul_f32_e32 v46, v46, v57
	v_mul_f32_e32 v47, v47, v49
	v_mul_f32_e32 v48, v40, v58
	v_mul_f32_e32 v49, v41, v50
	v_mul_f32_e32 v50, v42, v59
	v_cvt_pk_bf16_f32 v40, v44, v45
	v_cvt_pk_bf16_f32 v41, v46, v47
	v_cvt_pk_bf16_f32 v42, v48, v49
	v_cvt_pk_bf16_f32 v43, v50, v43
	global_store_dwordx4 v[54:55], v[40:43], off
	v_lshl_add_u64 v[46:47], v[106:107], 0, v[168:169]
	v_lshl_add_u64 v[44:45], v[104:105], 0, v[168:169]
	s_waitcnt vmcnt(16)
; __device__ __forceinline__ float bflo(unsigned w) { return __uint_as_float(w << 16); }
; __device__ __forceinline__ float bfhi(unsigned w) { return __uint_as_float(w & 0xffff0000u); }
; __device__ __forceinline__ unsigned pk2(float lo, float hi) { unsigned r; asm("v_cvt_pk_bf16_f32 %0, %1, %2" : "=v"(r) : "v"(lo), "v"(hi)); return r; }
; __device__ __forceinline__ float siluf_(float x) { return x * __builtin_amdgcn_rcpf(1.0f + __expf(-x)); }
;     __device__ __forceinline__ void operator()(const f32x4 (&acc)[2][2][4][2], const Unit& u, int wr, int wc, int fr, int fq) const {
;     ...
;             for (int ai = 0; ai < 2; ++ai)
; #pragma unroll
;                 for (int m = 0; m < 4; ++m) { const int row = row0 + ai * HALF + m * 16;
;                     const u32x4 z = __builtin_nontemporal_load((const u32x4*)(proj + (size_t)row * NPROJ + C_ZP + col));
;                     f32x4 v0 = (acc[ai][bj][m][0] + b0) * s0, v1 = (acc[ai][bj][m][1] + b1) * s1;
;                     v0[0] *= siluf_(bflo(z.x)); v0[1] *= siluf_(bfhi(z.x)); v0[2] *= siluf_(bflo(z.y)); v0[3] *= siluf_(bfhi(z.y));
;                     v1[0] *= siluf_(bflo(z.z)); v1[1] *= siluf_(bfhi(z.z)); v1[2] *= siluf_(bflo(z.w)); v1[3] *= siluf_(bfhi(z.w));
;                     u32x4 w; w.x = pk2(v0[0], v0[1]); w.y = pk2(v0[2], v0[3]); w.z = pk2(v1[0], v1[1]); w.w = pk2(v1[2], v1[3]);
;                     *(u32x4*)(a2 + (size_t)row * 4096 + 2048 + col) = w; } }
	v_mov_b32_e32 v40, v214
	v_mov_b32_e32 v41, v215
	v_mov_b32_e32 v42, v216
	v_mov_b32_e32 v43, v217
	v_lshlrev_b32_e32 v51, 16, v43
	v_and_b32_e32 v43, 0xffff0000, v43
	v_lshlrev_b32_e32 v48, 16, v40
	v_and_b32_e32 v40, 0xffff0000, v40
	v_lshlrev_b32_e32 v49, 16, v41
	v_and_b32_e32 v41, 0xffff0000, v41
	v_lshlrev_b32_e32 v50, 16, v42
	v_and_b32_e32 v42, 0xffff0000, v42
	v_mul_f32_e32 v59, 0xbfb8aa3b, v43
	v_mul_f32_e32 v52, 0xbfb8aa3b, v48
	v_mul_f32_e32 v53, 0xbfb8aa3b, v40
	v_mul_f32_e32 v54, 0xbfb8aa3b, v49
	v_mul_f32_e32 v55, 0xbfb8aa3b, v41
	v_mul_f32_e32 v56, 0xbfb8aa3b, v50
	v_mul_f32_e32 v57, 0xbfb8aa3b, v42
	v_mul_f32_e32 v58, 0xbfb8aa3b, v51
	v_exp_f32_e32 v59, v59
	v_exp_f32_e32 v52, v52
	v_exp_f32_e32 v53, v53
	v_exp_f32_e32 v54, v54
	v_exp_f32_e32 v55, v55
	v_exp_f32_e32 v56, v56
	v_exp_f32_e32 v57, v57
	v_exp_f32_e32 v58, v58
	v_add_f32_e32 v59, 1.0, v59
	v_add_f32_e32 v52, 1.0, v52
	v_add_f32_e32 v53, 1.0, v53
	v_add_f32_e32 v54, 1.0, v54
	v_add_f32_e32 v55, 1.0, v55
	v_add_f32_e32 v56, 1.0, v56
	v_add_f32_e32 v57, 1.0, v57
	v_add_f32_e32 v58, 1.0, v58
	v_rcp_f32_e32 v59, v59
	v_rcp_f32_e32 v52, v52
	v_rcp_f32_e32 v53, v53
	v_rcp_f32_e32 v54, v54
	v_rcp_f32_e32 v55, v55
	v_rcp_f32_e32 v56, v56
	v_rcp_f32_e32 v57, v57
	v_rcp_f32_e32 v58, v58
	v_mul_f32_e32 v43, v59, v43
	v_mul_f32_e32 v48, v52, v48
	v_mul_f32_e32 v40, v53, v40
	v_mul_f32_e32 v49, v54, v49
	v_mul_f32_e32 v41, v55, v41
	v_mul_f32_e32 v50, v56, v50
	v_mul_f32_e32 v42, v57, v42
	v_mul_f32_e32 v51, v58, v51
	v_mul_f32_e32 v35, v35, v43
	v_mul_f32_e32 v36, v36, v48
	v_mul_f32_e32 v37, v37, v40
	v_mul_f32_e32 v38, v38, v49
	v_mul_f32_e32 v39, v39, v41
	v_mul_f32_e32 v40, v32, v50
	v_mul_f32_e32 v41, v33, v42
	v_mul_f32_e32 v42, v34, v51
	v_cvt_pk_bf16_f32 v32, v36, v37
	v_cvt_pk_bf16_f32 v33, v38, v39
	v_cvt_pk_bf16_f32 v34, v40, v41
	v_cvt_pk_bf16_f32 v35, v42, v35
	global_store_dwordx4 v[46:47], v[32:35], off
	v_lshl_add_u64 v[38:39], v[98:99], 0, v[168:169]
	v_lshl_add_u64 v[36:37], v[96:97], 0, v[168:169]
	s_waitcnt vmcnt(15)
	v_mov_b32_e32 v32, v218
	v_mov_b32_e32 v33, v219
	v_mov_b32_e32 v34, v220
	v_mov_b32_e32 v35, v221
	v_lshlrev_b32_e32 v43, 16, v35
	v_and_b32_e32 v35, 0xffff0000, v35
	v_lshlrev_b32_e32 v40, 16, v32
	v_and_b32_e32 v32, 0xffff0000, v32
	v_lshlrev_b32_e32 v41, 16, v33
	v_and_b32_e32 v33, 0xffff0000, v33
	v_lshlrev_b32_e32 v42, 16, v34
	v_and_b32_e32 v34, 0xffff0000, v34
	v_mul_f32_e32 v51, 0xbfb8aa3b, v35
	v_mul_f32_e32 v44, 0xbfb8aa3b, v40
	v_mul_f32_e32 v45, 0xbfb8aa3b, v32
	v_mul_f32_e32 v46, 0xbfb8aa3b, v41
	v_mul_f32_e32 v47, 0xbfb8aa3b, v33
	v_mul_f32_e32 v48, 0xbfb8aa3b, v42
	v_mul_f32_e32 v49, 0xbfb8aa3b, v34
	v_mul_f32_e32 v50, 0xbfb8aa3b, v43
	v_exp_f32_e32 v51, v51
	v_exp_f32_e32 v44, v44
	v_exp_f32_e32 v45, v45
	v_exp_f32_e32 v46, v46
	v_exp_f32_e32 v47, v47
	v_exp_f32_e32 v48, v48
	v_exp_f32_e32 v49, v49
	v_exp_f32_e32 v50, v50
	v_add_f32_e32 v51, 1.0, v51
	v_add_f32_e32 v44, 1.0, v44
	v_add_f32_e32 v45, 1.0, v45
	v_add_f32_e32 v46, 1.0, v46
	v_add_f32_e32 v47, 1.0, v47
	v_add_f32_e32 v48, 1.0, v48
	v_add_f32_e32 v49, 1.0, v49
	v_add_f32_e32 v50, 1.0, v50
	v_rcp_f32_e32 v51, v51
	v_rcp_f32_e32 v44, v44
	v_rcp_f32_e32 v45, v45
	v_rcp_f32_e32 v46, v46
	v_rcp_f32_e32 v47, v47
	v_rcp_f32_e32 v48, v48
	v_rcp_f32_e32 v49, v49
	v_rcp_f32_e32 v50, v50
	v_mul_f32_e32 v35, v51, v35
	v_mul_f32_e32 v40, v44, v40
	v_mul_f32_e32 v32, v45, v32
	v_mul_f32_e32 v41, v46, v41
	v_mul_f32_e32 v33, v47, v33
	v_mul_f32_e32 v42, v48, v42
	v_mul_f32_e32 v34, v49, v34
	v_mul_f32_e32 v43, v50, v43
	v_mul_f32_e32 v27, v27, v35
	v_mul_f32_e32 v28, v28, v40
	v_mul_f32_e32 v29, v29, v32
	v_mul_f32_e32 v30, v30, v41
	v_mul_f32_e32 v31, v31, v33
	v_mul_f32_e32 v32, v24, v42
	v_mul_f32_e32 v33, v25, v34
	v_mul_f32_e32 v34, v26, v43
	v_cvt_pk_bf16_f32 v24, v28, v29
	v_cvt_pk_bf16_f32 v25, v30, v31
	v_cvt_pk_bf16_f32 v26, v32, v33
	v_cvt_pk_bf16_f32 v27, v34, v27
	global_store_dwordx4 v[38:39], v[24:27], off
	v_lshl_add_u64 v[30:31], v[90:91], 0, v[168:169]
	v_lshl_add_u64 v[28:29], v[88:89], 0, v[168:169]
	s_waitcnt vmcnt(14)
; __device__ __forceinline__ float bflo(unsigned w) { return __uint_as_float(w << 16); }
; __device__ __forceinline__ float bfhi(unsigned w) { return __uint_as_float(w & 0xffff0000u); }
; __device__ __forceinline__ unsigned pk2(float lo, float hi) { unsigned r; asm("v_cvt_pk_bf16_f32 %0, %1, %2" : "=v"(r) : "v"(lo), "v"(hi)); return r; }
; __device__ __forceinline__ float siluf_(float x) { return x * __builtin_amdgcn_rcpf(1.0f + __expf(-x)); }
; #define PG8_WAIT_V(n) asm volatile("s_waitcnt vmcnt(" #n ")" ::: "memory")
; #define PG8_BAR __builtin_amdgcn_s_barrier()
; template <class Epi>
; __device__ __forceinline__ void gemm_phase(LAS unsigned char* lds, const GemmD g, const Epi& E) {
;     ...
;     PG8_WAIT_V(0);
;     if (wr == 0) PG8_BAR;
;     PG8_BAR;
;     __device__ __forceinline__ void operator()(const f32x4 (&acc)[2][2][4][2], const Unit& u, int wr, int wc, int fr, int fq) const {
;     ...
;                 for (int m = 0; m < 4; ++m) { const int row = row0 + ai * HALF + m * 16;
;                     const u32x4 z = __builtin_nontemporal_load((const u32x4*)(proj + (size_t)row * NPROJ + C_ZP + col));
;                     f32x4 v0 = (acc[ai][bj][m][0] + b0) * s0, v1 = (acc[ai][bj][m][1] + b1) * s1;
;                     v0[0] *= siluf_(bflo(z.x)); v0[1] *= siluf_(bfhi(z.x)); v0[2] *= siluf_(bflo(z.y)); v0[3] *= siluf_(bfhi(z.y));
;                     v1[0] *= siluf_(bflo(z.z)); v1[1] *= siluf_(bfhi(z.z)); v1[2] *= siluf_(bflo(z.w)); v1[3] *= siluf_(bfhi(z.w));
;                     u32x4 w; w.x = pk2(v0[0], v0[1]); w.y = pk2(v0[2], v0[3]); w.z = pk2(v1[0], v1[1]); w.w = pk2(v1[2], v1[3]);
;                     *(u32x4*)(a2 + (size_t)row * 4096 + 2048 + col) = w; } }
	v_mov_b32_e32 v24, v222
	v_mov_b32_e32 v25, v223
	v_mov_b32_e32 v26, v224
	v_mov_b32_e32 v27, v225
	v_lshlrev_b32_e32 v35, 16, v27
	v_and_b32_e32 v27, 0xffff0000, v27
	v_lshlrev_b32_e32 v32, 16, v24
	v_and_b32_e32 v24, 0xffff0000, v24
	v_lshlrev_b32_e32 v33, 16, v25
	v_and_b32_e32 v25, 0xffff0000, v25
	v_lshlrev_b32_e32 v34, 16, v26
	v_and_b32_e32 v26, 0xffff0000, v26
	v_mul_f32_e32 v43, 0xbfb8aa3b, v27
	v_mul_f32_e32 v36, 0xbfb8aa3b, v32
	v_mul_f32_e32 v37, 0xbfb8aa3b, v24
	v_mul_f32_e32 v38, 0xbfb8aa3b, v33
	v_mul_f32_e32 v39, 0xbfb8aa3b, v25
	v_mul_f32_e32 v40, 0xbfb8aa3b, v34
	v_mul_f32_e32 v41, 0xbfb8aa3b, v26
	v_mul_f32_e32 v42, 0xbfb8aa3b, v35
	v_exp_f32_e32 v43, v43
	v_exp_f32_e32 v36, v36
	v_exp_f32_e32 v37, v37
	v_exp_f32_e32 v38, v38
	v_exp_f32_e32 v39, v39
	v_exp_f32_e32 v40, v40
	v_exp_f32_e32 v41, v41
	v_exp_f32_e32 v42, v42
	v_add_f32_e32 v43, 1.0, v43
	v_add_f32_e32 v36, 1.0, v36
	v_add_f32_e32 v37, 1.0, v37
	v_add_f32_e32 v38, 1.0, v38
	v_add_f32_e32 v39, 1.0, v39
	v_add_f32_e32 v40, 1.0, v40
	v_add_f32_e32 v41, 1.0, v41
	v_add_f32_e32 v42, 1.0, v42
	v_rcp_f32_e32 v43, v43
	v_rcp_f32_e32 v36, v36
	v_rcp_f32_e32 v37, v37
	v_rcp_f32_e32 v38, v38
	v_rcp_f32_e32 v39, v39
	v_rcp_f32_e32 v40, v40
	v_rcp_f32_e32 v41, v41
	v_rcp_f32_e32 v42, v42
	v_mul_f32_e32 v27, v43, v27
	v_mul_f32_e32 v32, v36, v32
	v_mul_f32_e32 v24, v37, v24
	v_mul_f32_e32 v33, v38, v33
	v_mul_f32_e32 v25, v39, v25
	v_mul_f32_e32 v34, v40, v34
	v_mul_f32_e32 v26, v41, v26
	v_mul_f32_e32 v35, v42, v35
	v_mul_f32_e32 v19, v19, v27
	v_mul_f32_e32 v20, v20, v32
	v_mul_f32_e32 v21, v21, v24
	v_mul_f32_e32 v22, v22, v33
	v_mul_f32_e32 v23, v23, v25
	v_mul_f32_e32 v24, v16, v34
	v_mul_f32_e32 v25, v17, v26
	v_mul_f32_e32 v26, v18, v35
	v_cvt_pk_bf16_f32 v16, v20, v21
	v_cvt_pk_bf16_f32 v17, v22, v23
	v_cvt_pk_bf16_f32 v18, v24, v25
	v_cvt_pk_bf16_f32 v19, v26, v19
	global_store_dwordx4 v[30:31], v[16:19], off
	v_lshl_add_u64 v[22:23], v[84:85], 0, v[168:169]
	v_lshl_add_u64 v[20:21], v[82:83], 0, v[168:169]
	s_waitcnt vmcnt(13)
	v_mov_b32_e32 v16, v226
	v_mov_b32_e32 v17, v227
	v_mov_b32_e32 v18, v228
	v_mov_b32_e32 v19, v229
	v_lshlrev_b32_e32 v27, 16, v19
	v_and_b32_e32 v19, 0xffff0000, v19
	v_lshlrev_b32_e32 v24, 16, v16
	v_and_b32_e32 v16, 0xffff0000, v16
	v_lshlrev_b32_e32 v25, 16, v17
	v_and_b32_e32 v17, 0xffff0000, v17
	v_lshlrev_b32_e32 v26, 16, v18
	v_and_b32_e32 v18, 0xffff0000, v18
	v_mul_f32_e32 v35, 0xbfb8aa3b, v19
	v_mul_f32_e32 v28, 0xbfb8aa3b, v24
	v_mul_f32_e32 v29, 0xbfb8aa3b, v16
	v_mul_f32_e32 v30, 0xbfb8aa3b, v25
	v_mul_f32_e32 v31, 0xbfb8aa3b, v17
	v_mul_f32_e32 v32, 0xbfb8aa3b, v26
	v_mul_f32_e32 v33, 0xbfb8aa3b, v18
	v_mul_f32_e32 v34, 0xbfb8aa3b, v27
	v_exp_f32_e32 v35, v35
	v_exp_f32_e32 v28, v28
	v_exp_f32_e32 v29, v29
	v_exp_f32_e32 v30, v30
	v_exp_f32_e32 v31, v31
	v_exp_f32_e32 v32, v32
	v_exp_f32_e32 v33, v33
	v_exp_f32_e32 v34, v34
	v_add_f32_e32 v35, 1.0, v35
	v_add_f32_e32 v28, 1.0, v28
	v_add_f32_e32 v29, 1.0, v29
	v_add_f32_e32 v30, 1.0, v30
	v_add_f32_e32 v31, 1.0, v31
	v_add_f32_e32 v32, 1.0, v32
	v_add_f32_e32 v33, 1.0, v33
	v_add_f32_e32 v34, 1.0, v34
	v_rcp_f32_e32 v35, v35
	v_rcp_f32_e32 v28, v28
	v_rcp_f32_e32 v29, v29
	v_rcp_f32_e32 v30, v30
	v_rcp_f32_e32 v31, v31
	v_rcp_f32_e32 v32, v32
	v_rcp_f32_e32 v33, v33
	v_rcp_f32_e32 v34, v34
	v_mul_f32_e32 v19, v35, v19
	v_mul_f32_e32 v24, v28, v24
	v_mul_f32_e32 v16, v29, v16
	v_mul_f32_e32 v25, v30, v25
	v_mul_f32_e32 v17, v31, v17
	v_mul_f32_e32 v26, v32, v26
	v_mul_f32_e32 v18, v33, v18
	v_mul_f32_e32 v27, v34, v27
	v_mul_f32_e32 v11, v11, v19
	v_mul_f32_e32 v12, v12, v24
	v_mul_f32_e32 v13, v13, v16
	v_mul_f32_e32 v14, v14, v25
	v_mul_f32_e32 v15, v15, v17
	v_mul_f32_e32 v16, v8, v26
	v_mul_f32_e32 v17, v9, v18
	v_mul_f32_e32 v18, v10, v27
	v_cvt_pk_bf16_f32 v8, v12, v13
	v_cvt_pk_bf16_f32 v9, v14, v15
	v_cvt_pk_bf16_f32 v10, v16, v17
	v_cvt_pk_bf16_f32 v11, v18, v11
	global_store_dwordx4 v[22:23], v[8:11], off
	v_lshl_add_u64 v[12:13], v[80:81], 0, v[168:169]
	s_waitcnt vmcnt(12)
	v_mov_b32_e32 v8, v230
	v_mov_b32_e32 v9, v231
	v_mov_b32_e32 v10, v232
	v_mov_b32_e32 v11, v233
	v_lshlrev_b32_e32 v17, 16, v11
	v_and_b32_e32 v11, 0xffff0000, v11
	v_lshlrev_b32_e32 v14, 16, v8
	v_and_b32_e32 v8, 0xffff0000, v8
	v_lshlrev_b32_e32 v15, 16, v9
	v_and_b32_e32 v9, 0xffff0000, v9
	v_lshlrev_b32_e32 v16, 16, v10
	v_and_b32_e32 v10, 0xffff0000, v10
	v_mul_f32_e32 v25, 0xbfb8aa3b, v11
	v_mul_f32_e32 v18, 0xbfb8aa3b, v14
	v_mul_f32_e32 v19, 0xbfb8aa3b, v8
	v_mul_f32_e32 v20, 0xbfb8aa3b, v15
	v_mul_f32_e32 v21, 0xbfb8aa3b, v9
	v_mul_f32_e32 v22, 0xbfb8aa3b, v16
	v_mul_f32_e32 v23, 0xbfb8aa3b, v10
	v_mul_f32_e32 v24, 0xbfb8aa3b, v17
	v_exp_f32_e32 v25, v25
	v_exp_f32_e32 v18, v18
	v_exp_f32_e32 v19, v19
	v_exp_f32_e32 v20, v20
	v_exp_f32_e32 v21, v21
	v_exp_f32_e32 v22, v22
	v_exp_f32_e32 v23, v23
	v_exp_f32_e32 v24, v24
	v_add_f32_e32 v25, 1.0, v25
	v_add_f32_e32 v18, 1.0, v18
	v_add_f32_e32 v19, 1.0, v19
	v_add_f32_e32 v20, 1.0, v20
	v_add_f32_e32 v21, 1.0, v21
	v_add_f32_e32 v22, 1.0, v22
	v_add_f32_e32 v23, 1.0, v23
	v_add_f32_e32 v24, 1.0, v24
	v_rcp_f32_e32 v25, v25
	v_rcp_f32_e32 v18, v18
	v_rcp_f32_e32 v19, v19
	v_rcp_f32_e32 v20, v20
	v_rcp_f32_e32 v21, v21
	v_rcp_f32_e32 v22, v22
	v_rcp_f32_e32 v23, v23
	v_rcp_f32_e32 v24, v24
	v_mul_f32_e32 v11, v25, v11
	v_mul_f32_e32 v14, v18, v14
	v_mul_f32_e32 v8, v19, v8
	v_mul_f32_e32 v15, v20, v15
	v_mul_f32_e32 v9, v21, v9
	v_mul_f32_e32 v16, v22, v16
	v_mul_f32_e32 v10, v23, v10
	v_mul_f32_e32 v17, v24, v17
	v_mul_f32_e32 v3, v3, v11
	v_mul_f32_e32 v4, v4, v14
	v_mul_f32_e32 v5, v5, v8
	v_mul_f32_e32 v6, v6, v15
	v_mul_f32_e32 v7, v7, v9
	v_mul_f32_e32 v8, v0, v16
	v_mul_f32_e32 v9, v1, v10
	v_mul_f32_e32 v10, v2, v17
	v_cvt_pk_bf16_f32 v0, v4, v5
	v_cvt_pk_bf16_f32 v1, v6, v7
	v_cvt_pk_bf16_f32 v2, v8, v9
	v_cvt_pk_bf16_f32 v3, v10, v3
	global_store_dwordx4 v[12:13], v[0:3], off
	s_cbranch_vccz .LBB0_595
	s_waitcnt vmcnt(0)
	s_cmpk_gt_u32 s33, 0xff
	s_cbranch_scc1 .LBB0_604
	s_barrier

.LBB0_903:
	s_add_u32 s24, s30, 0xfff00080
	s_addc_u32 s25, s31, -1
	s_add_i32 s29, 0, 0x10000
	v_add_u32_e32 v0, s29, v204
	ds_read_b128 v[132:135], v0
	ds_read_b128 v[136:139], v0 offset:1024
	ds_read_b128 v[140:143], v0 offset:2048
	ds_read_b128 v[144:147], v0 offset:3072
	s_cmp_eq_u32 s27, 28
	s_cselect_b32 s35, s1, s25
	s_cselect_b32 s34, s0, s24
	s_cselect_b32 s25, s39, s3
	s_cselect_b32 s24, s38, s2
	v_lshl_add_u64 v[2:3], s[30:31], 0, v[188:189]
	s_add_i32 m0, s46, 0xc000
	ds_read_b128 v[148:151], v206
	ds_read_b128 v[152:155], v206 offset:1024
	ds_read_b128 v[156:159], v206 offset:2048
	ds_read_b128 v[160:163], v206 offset:3072
	ds_read_b128 v[164:167], v206 offset:4096
	ds_read_b128 v[168:171], v206 offset:5120
	ds_read_b128 v[208:211], v206 offset:6144
	ds_read_b128 v[212:215], v206 offset:7168
	global_load_lds_dwordx4 v[2:3], off
	v_lshl_add_u64 v[2:3], s[30:31], 0, v[190:191]
	s_add_i32 m0, s46, 0xe000
	s_nop 0
	global_load_lds_dwordx4 v[2:3], off
	s_waitcnt lgkmcnt(8)
	s_barrier
	s_waitcnt lgkmcnt(0)
	s_setprio 1
	s_waitcnt lgkmcnt(0)
	v_mfma_f32_16x16x32_bf16 v[2:5], v[132:135], v[148:151], v[4:7]
	v_mfma_f32_16x16x32_bf16 v[6:9], v[140:143], v[148:151], v[8:11]
	v_mfma_f32_16x16x32_bf16 v[12:15], v[132:135], v[156:159], v[12:15]
	v_mfma_f32_16x16x32_bf16 v[16:19], v[140:143], v[156:159], v[16:19]
	v_mfma_f32_16x16x32_bf16 v[20:23], v[132:135], v[164:167], v[20:23]
	v_mfma_f32_16x16x32_bf16 v[24:27], v[140:143], v[164:167], v[24:27]
	v_mfma_f32_16x16x32_bf16 v[28:31], v[132:135], v[208:211], v[28:31]
	v_mfma_f32_16x16x32_bf16 v[32:35], v[140:143], v[208:211], v[32:35]
	v_mfma_f32_16x16x32_bf16 v[2:5], v[136:139], v[152:155], v[2:5]
	v_mfma_f32_16x16x32_bf16 v[8:11], v[144:147], v[152:155], v[6:9]
	v_mfma_f32_16x16x32_bf16 v[12:15], v[136:139], v[160:163], v[12:15]
	v_mfma_f32_16x16x32_bf16 v[16:19], v[144:147], v[160:163], v[16:19]
	v_mfma_f32_16x16x32_bf16 v[20:23], v[136:139], v[168:171], v[20:23]
	v_mfma_f32_16x16x32_bf16 v[24:27], v[144:147], v[168:171], v[24:27]
	v_mfma_f32_16x16x32_bf16 v[28:31], v[136:139], v[212:215], v[28:31]
	v_mfma_f32_16x16x32_bf16 v[32:35], v[144:147], v[212:215], v[32:35]
	s_setprio 0
	s_barrier
	s_add_i32 s73, 0, 0x14000
	s_add_i32 s29, s29, s41
	v_add_u32_e32 v0, s73, v204
	v_lshl_add_u64 v[232:233], s[24:25], 0, v[184:185]
	s_mov_b32 m0, s29
	ds_read_b128 v[216:219], v0
	ds_read_b128 v[220:223], v0 offset:1024
	ds_read_b128 v[224:227], v0 offset:2048
	ds_read_b128 v[228:231], v0 offset:3072
	global_load_lds_dwordx4 v[232:233], off
	v_lshl_add_u64 v[234:235], s[24:25], 0, v[180:181]
	s_add_i32 m0, s29, 0x2000
	s_nop 0
	global_load_lds_dwordx4 v[234:235], off
	s_barrier
	s_waitcnt lgkmcnt(0)
	s_setprio 1
	s_waitcnt lgkmcnt(0)
	v_mfma_f32_16x16x32_bf16 v[36:39], v[216:219], v[148:151], v[36:39]
	v_mfma_f32_16x16x32_bf16 v[40:43], v[224:227], v[148:151], v[40:43]
	v_mfma_f32_16x16x32_bf16 v[44:47], v[216:219], v[156:159], v[44:47]
	v_mfma_f32_16x16x32_bf16 v[48:51], v[224:227], v[156:159], v[48:51]
	v_mfma_f32_16x16x32_bf16 v[52:55], v[216:219], v[164:167], v[52:55]
	v_mfma_f32_16x16x32_bf16 v[56:59], v[224:227], v[164:167], v[56:59]
	v_mfma_f32_16x16x32_bf16 v[60:63], v[216:219], v[208:211], v[60:63]
	v_mfma_f32_16x16x32_bf16 v[64:67], v[224:227], v[208:211], v[64:67]
	v_mfma_f32_16x16x32_bf16 v[36:39], v[220:223], v[152:155], v[36:39]
	v_mfma_f32_16x16x32_bf16 v[40:43], v[228:231], v[152:155], v[40:43]
	v_mfma_f32_16x16x32_bf16 v[44:47], v[220:223], v[160:163], v[44:47]
	v_mfma_f32_16x16x32_bf16 v[48:51], v[228:231], v[160:163], v[48:51]
	v_mfma_f32_16x16x32_bf16 v[52:55], v[220:223], v[168:171], v[52:55]
	v_mfma_f32_16x16x32_bf16 v[56:59], v[228:231], v[168:171], v[56:59]
	v_mfma_f32_16x16x32_bf16 v[60:63], v[220:223], v[212:215], v[60:63]
	v_mfma_f32_16x16x32_bf16 v[64:67], v[228:231], v[212:215], v[64:67]
	s_setprio 0
	s_mov_b32 m0, s46
	v_lshl_add_u64 v[236:237], s[34:35], 0, v[186:187]
	s_barrier
	ds_read_b128 v[148:151], v206 offset:16384
	ds_read_b128 v[152:155], v206 offset:17408
	ds_read_b128 v[156:159], v206 offset:18432
	ds_read_b128 v[160:163], v206 offset:19456
	ds_read_b128 v[164:167], v206 offset:20480
	ds_read_b128 v[168:171], v206 offset:21504
	ds_read_b128 v[208:211], v206 offset:22528
	ds_read_b128 v[212:215], v206 offset:23552
	global_load_lds_dwordx4 v[236:237], off
	v_lshl_add_u64 v[238:239], s[34:35], 0, v[182:183]
	s_mov_b32 m0, s47
	s_nop 0
	global_load_lds_dwordx4 v[238:239], off
	s_barrier
	s_waitcnt lgkmcnt(0)
	s_setprio 1
	s_waitcnt lgkmcnt(0)
	v_mfma_f32_16x16x32_bf16 v[68:71], v[132:135], v[148:151], v[68:71]
	v_mfma_f32_16x16x32_bf16 v[72:75], v[140:143], v[148:151], v[72:75]
	v_mfma_f32_16x16x32_bf16 v[76:79], v[132:135], v[156:159], v[76:79]
	v_mfma_f32_16x16x32_bf16 v[80:83], v[140:143], v[156:159], v[80:83]
	v_mfma_f32_16x16x32_bf16 v[84:87], v[132:135], v[164:167], v[84:87]
	v_mfma_f32_16x16x32_bf16 v[88:91], v[140:143], v[164:167], v[88:91]
	v_mfma_f32_16x16x32_bf16 v[92:95], v[132:135], v[208:211], v[92:95]
	v_mfma_f32_16x16x32_bf16 v[96:99], v[140:143], v[208:211], v[96:99]
	v_mfma_f32_16x16x32_bf16 v[68:71], v[136:139], v[152:155], v[68:71]
	v_mfma_f32_16x16x32_bf16 v[72:75], v[144:147], v[152:155], v[72:75]
	v_mfma_f32_16x16x32_bf16 v[76:79], v[136:139], v[160:163], v[76:79]
	v_mfma_f32_16x16x32_bf16 v[80:83], v[144:147], v[160:163], v[80:83]
	v_mfma_f32_16x16x32_bf16 v[84:87], v[136:139], v[168:171], v[84:87]
	v_mfma_f32_16x16x32_bf16 v[88:91], v[144:147], v[168:171], v[88:91]
	v_mfma_f32_16x16x32_bf16 v[92:95], v[136:139], v[212:215], v[92:95]
	v_mfma_f32_16x16x32_bf16 v[96:99], v[144:147], v[212:215], v[96:99]
	s_setprio 0
	s_barrier
	s_add_u32 s74, s24, 0x100000
	s_addc_u32 s75, s25, 0
	s_add_i32 s29, s73, s41
	v_lshl_add_u64 v[6:7], s[74:75], 0, v[184:185]
	s_mov_b32 m0, s29
	s_nop 0
	global_load_lds_dwordx4 v[6:7], off
	v_lshl_add_u64 v[6:7], s[74:75], 0, v[180:181]
	s_add_i32 m0, s29, 0x2000
	s_nop 0
	global_load_lds_dwordx4 v[6:7], off
	s_waitcnt vmcnt(6)
	s_barrier
	s_setprio 1
	v_mfma_f32_16x16x32_bf16 v[100:103], v[216:219], v[148:151], v[100:103]
	v_mfma_f32_16x16x32_bf16 v[104:107], v[224:227], v[148:151], v[104:107]
	v_mfma_f32_16x16x32_bf16 v[108:111], v[216:219], v[156:159], v[108:111]
	v_mfma_f32_16x16x32_bf16 v[112:115], v[224:227], v[156:159], v[112:115]
	v_mfma_f32_16x16x32_bf16 v[116:119], v[216:219], v[164:167], v[116:119]
	v_mfma_f32_16x16x32_bf16 v[120:123], v[224:227], v[164:167], v[120:123]
	v_mfma_f32_16x16x32_bf16 v[124:127], v[216:219], v[208:211], v[124:127]
	v_mfma_f32_16x16x32_bf16 v[128:131], v[224:227], v[208:211], v[128:131]
	v_mfma_f32_16x16x32_bf16 v[100:103], v[220:223], v[152:155], v[100:103]
	v_mfma_f32_16x16x32_bf16 v[104:107], v[228:231], v[152:155], v[104:107]
	v_mfma_f32_16x16x32_bf16 v[108:111], v[220:223], v[160:163], v[108:111]
	v_mfma_f32_16x16x32_bf16 v[112:115], v[228:231], v[160:163], v[112:115]
	v_mfma_f32_16x16x32_bf16 v[116:119], v[220:223], v[168:171], v[116:119]
	v_mfma_f32_16x16x32_bf16 v[120:123], v[228:231], v[168:171], v[120:123]
	v_mfma_f32_16x16x32_bf16 v[124:127], v[220:223], v[212:215], v[124:127]
	v_mfma_f32_16x16x32_bf16 v[128:131], v[228:231], v[212:215], v[128:131]
	s_setprio 0
	s_add_i32 s29, 0, 0x18000
	v_add_u32_e32 v0, s29, v204
	s_barrier
	ds_read_b128 v[132:135], v0
	ds_read_b128 v[136:139], v0 offset:1024
	ds_read_b128 v[140:143], v0 offset:2048
	ds_read_b128 v[144:147], v0 offset:3072
	s_add_u32 s34, s34, 0x100000
	s_addc_u32 s35, s35, 0
	s_mov_b32 m0, s50
	v_lshl_add_u64 v[6:7], s[34:35], 0, v[186:187]
	ds_read_b128 v[148:151], v206 offset:32768
	ds_read_b128 v[152:155], v206 offset:33792
	ds_read_b128 v[156:159], v206 offset:34816
	ds_read_b128 v[160:163], v206 offset:35840
	ds_read_b128 v[164:167], v206 offset:36864
	ds_read_b128 v[168:171], v206 offset:37888
	ds_read_b128 v[208:211], v206 offset:38912
	ds_read_b128 v[212:215], v206 offset:39936
	global_load_lds_dwordx4 v[6:7], off
	v_lshl_add_u64 v[6:7], s[34:35], 0, v[182:183]
	s_mov_b32 m0, s51
	s_nop 0
	global_load_lds_dwordx4 v[6:7], off
	s_waitcnt lgkmcnt(8)
	s_barrier
	s_waitcnt lgkmcnt(0)
	s_setprio 1
	s_waitcnt lgkmcnt(0)
	v_mfma_f32_16x16x32_bf16 v[2:5], v[132:135], v[148:151], v[2:5]
	v_mfma_f32_16x16x32_bf16 v[8:11], v[140:143], v[148:151], v[8:11]
	v_mfma_f32_16x16x32_bf16 v[12:15], v[132:135], v[156:159], v[12:15]
	v_mfma_f32_16x16x32_bf16 v[16:19], v[140:143], v[156:159], v[16:19]
	v_mfma_f32_16x16x32_bf16 v[20:23], v[132:135], v[164:167], v[20:23]
	v_mfma_f32_16x16x32_bf16 v[24:27], v[140:143], v[164:167], v[24:27]
	v_mfma_f32_16x16x32_bf16 v[28:31], v[132:135], v[208:211], v[28:31]
	v_mfma_f32_16x16x32_bf16 v[32:35], v[140:143], v[208:211], v[32:35]
	v_mfma_f32_16x16x32_bf16 v[4:7], v[136:139], v[152:155], v[2:5]
	v_mfma_f32_16x16x32_bf16 v[8:11], v[144:147], v[152:155], v[8:11]
	v_mfma_f32_16x16x32_bf16 v[12:15], v[136:139], v[160:163], v[12:15]
	v_mfma_f32_16x16x32_bf16 v[16:19], v[144:147], v[160:163], v[16:19]
	v_mfma_f32_16x16x32_bf16 v[20:23], v[136:139], v[168:171], v[20:23]
	v_mfma_f32_16x16x32_bf16 v[24:27], v[144:147], v[168:171], v[24:27]
	v_mfma_f32_16x16x32_bf16 v[28:31], v[136:139], v[212:215], v[28:31]
	v_mfma_f32_16x16x32_bf16 v[32:35], v[144:147], v[212:215], v[32:35]
	s_setprio 0
	s_barrier
	s_add_i32 s34, 0, 0x1c000
	s_add_i32 s29, s29, s41
	v_add_u32_e32 v0, s34, v204
	v_lshl_add_u64 v[2:3], v[232:233], 0, s[48:49]
	s_mov_b32 m0, s29
	ds_read_b128 v[216:219], v0
	ds_read_b128 v[220:223], v0 offset:1024
	ds_read_b128 v[224:227], v0 offset:2048
	ds_read_b128 v[228:231], v0 offset:3072
	global_load_lds_dwordx4 v[2:3], off
	v_lshl_add_u64 v[2:3], v[234:235], 0, s[48:49]
	s_add_i32 m0, s29, 0x2000
	s_nop 0
	global_load_lds_dwordx4 v[2:3], off
	s_barrier
	s_waitcnt lgkmcnt(0)
	s_setprio 1
	s_waitcnt lgkmcnt(0)
	v_mfma_f32_16x16x32_bf16 v[36:39], v[216:219], v[148:151], v[36:39]
	v_mfma_f32_16x16x32_bf16 v[40:43], v[224:227], v[148:151], v[40:43]
	v_mfma_f32_16x16x32_bf16 v[44:47], v[216:219], v[156:159], v[44:47]
	v_mfma_f32_16x16x32_bf16 v[48:51], v[224:227], v[156:159], v[48:51]
	v_mfma_f32_16x16x32_bf16 v[52:55], v[216:219], v[164:167], v[52:55]
	v_mfma_f32_16x16x32_bf16 v[56:59], v[224:227], v[164:167], v[56:59]
	v_mfma_f32_16x16x32_bf16 v[60:63], v[216:219], v[208:211], v[60:63]
	v_mfma_f32_16x16x32_bf16 v[64:67], v[224:227], v[208:211], v[64:67]
	v_mfma_f32_16x16x32_bf16 v[36:39], v[220:223], v[152:155], v[36:39]
	v_mfma_f32_16x16x32_bf16 v[40:43], v[228:231], v[152:155], v[40:43]
	v_mfma_f32_16x16x32_bf16 v[44:47], v[220:223], v[160:163], v[44:47]
	v_mfma_f32_16x16x32_bf16 v[48:51], v[228:231], v[160:163], v[48:51]
	v_mfma_f32_16x16x32_bf16 v[52:55], v[220:223], v[168:171], v[52:55]
	v_mfma_f32_16x16x32_bf16 v[56:59], v[228:231], v[168:171], v[56:59]
	v_mfma_f32_16x16x32_bf16 v[60:63], v[220:223], v[212:215], v[60:63]
	v_mfma_f32_16x16x32_bf16 v[64:67], v[228:231], v[212:215], v[64:67]
	s_setprio 0
	s_mov_b32 m0, s56
	v_lshl_add_u64 v[2:3], v[236:237], 0, s[48:49]
	s_barrier
	ds_read_b128 v[148:151], v206 offset:49152
	ds_read_b128 v[152:155], v206 offset:50176
	ds_read_b128 v[156:159], v206 offset:51200
	ds_read_b128 v[160:163], v206 offset:52224
	ds_read_b128 v[164:167], v206 offset:53248
	ds_read_b128 v[168:171], v206 offset:54272
	ds_read_b128 v[208:211], v206 offset:55296
	ds_read_b128 v[212:215], v206 offset:56320
	global_load_lds_dwordx4 v[2:3], off
	v_lshl_add_u64 v[2:3], v[238:239], 0, s[48:49]
	s_mov_b32 m0, s57
	s_nop 0
	global_load_lds_dwordx4 v[2:3], off
	s_barrier
; __device__ __forceinline__ float bflo(unsigned w) { return __uint_as_float(w << 16); }
; __device__ __forceinline__ float bfhi(unsigned w) { return __uint_as_float(w & 0xffff0000u); }
; __device__ __forceinline__ unsigned pk2(float lo, float hi) { unsigned r; asm("v_cvt_pk_bf16_f32 %0, %1, %2" : "=v"(r) : "v"(lo), "v"(hi)); return r; }
; template <class Epi>
; __device__ __forceinline__ void gemm_phase(LAS unsigned char* lds, const GemmD g, const Epi& E) {
;     ...
;         for (int t = 0; t < nt; t += 2) PG8_KITER(t);
;     __device__ __forceinline__ void operator()(const f32x4 (&acc)[2][2][4][2], const Unit& u, int wr, int wc, int fr, int fq) const {
;         const int row0 = u.pm * BM + wr * 64 + fr, col0 = u.pn * BM + wc * 32 + 8 * fq;
; #pragma unroll
;         for (int ai = 0; ai < 2; ++ai)
; #pragma unroll
;             for (int m = 0; m < 4; ++m) { const int row = row0 + ai * HALF + m * 16;
; #pragma unroll
;                 for (int bj = 0; bj < 2; ++bj) { const int col = col0 + bj * HALF;
;                     const u32x4 gp = *(const u32x4*)(proj + (size_t)row * NPROJ + C_GP + col);
;                     const f32x4 v0 = acc[ai][bj][m][0], v1 = acc[ai][bj][m][1];
;                     u32x4 w; w.x = pk2(v0[0] * bflo(gp.x), v0[1] * bfhi(gp.x)); w.y = pk2(v0[2] * bflo(gp.y), v0[3] * bfhi(gp.y));
;                     w.z = pk2(v1[0] * bflo(gp.z), v1[1] * bfhi(gp.z)); w.w = pk2(v1[2] * bflo(gp.w), v1[3] * bfhi(gp.w));
;                     *(u32x4*)(merged + (size_t)row * DM + col) = w; } }
	s_waitcnt lgkmcnt(0)
	s_setprio 1
	s_waitcnt lgkmcnt(0)
	v_mfma_f32_16x16x32_bf16 v[68:71], v[132:135], v[148:151], v[68:71]
	v_mfma_f32_16x16x32_bf16 v[72:75], v[140:143], v[148:151], v[72:75]
	v_mfma_f32_16x16x32_bf16 v[76:79], v[132:135], v[156:159], v[76:79]
	v_mfma_f32_16x16x32_bf16 v[80:83], v[140:143], v[156:159], v[80:83]
	v_mfma_f32_16x16x32_bf16 v[84:87], v[132:135], v[164:167], v[84:87]
	v_mfma_f32_16x16x32_bf16 v[88:91], v[140:143], v[164:167], v[88:91]
	v_mfma_f32_16x16x32_bf16 v[92:95], v[132:135], v[208:211], v[92:95]
	v_mfma_f32_16x16x32_bf16 v[96:99], v[140:143], v[208:211], v[96:99]
	v_mfma_f32_16x16x32_bf16 v[68:71], v[136:139], v[152:155], v[68:71]
	v_mfma_f32_16x16x32_bf16 v[72:75], v[144:147], v[152:155], v[72:75]
	v_mfma_f32_16x16x32_bf16 v[76:79], v[136:139], v[160:163], v[76:79]
	v_mfma_f32_16x16x32_bf16 v[80:83], v[144:147], v[160:163], v[80:83]
	v_mfma_f32_16x16x32_bf16 v[84:87], v[136:139], v[168:171], v[84:87]
	v_mfma_f32_16x16x32_bf16 v[88:91], v[144:147], v[168:171], v[88:91]
	v_mfma_f32_16x16x32_bf16 v[92:95], v[136:139], v[212:215], v[92:95]
	v_mfma_f32_16x16x32_bf16 v[96:99], v[144:147], v[212:215], v[96:99]
	s_setprio 0
	s_barrier
	s_add_u32 s24, s24, 0x100080
	s_addc_u32 s25, s25, 0
	s_add_i32 s29, s34, s41
	v_lshl_add_u64 v[2:3], s[24:25], 0, v[184:185]
	s_mov_b32 m0, s29
	s_nop 0
	global_load_lds_dwordx4 v[2:3], off
	v_lshl_add_u64 v[2:3], s[24:25], 0, v[180:181]
	s_add_i32 m0, s29, 0x2000
	s_nop 0
	global_load_lds_dwordx4 v[2:3], off
	s_waitcnt vmcnt(6)
	s_barrier
	s_setprio 1
	v_mfma_f32_16x16x32_bf16 v[100:103], v[216:219], v[148:151], v[100:103]
	v_mfma_f32_16x16x32_bf16 v[104:107], v[224:227], v[148:151], v[104:107]
	v_mfma_f32_16x16x32_bf16 v[108:111], v[216:219], v[156:159], v[108:111]
	v_mfma_f32_16x16x32_bf16 v[112:115], v[224:227], v[156:159], v[112:115]
	v_mfma_f32_16x16x32_bf16 v[116:119], v[216:219], v[164:167], v[116:119]
	v_mfma_f32_16x16x32_bf16 v[120:123], v[224:227], v[164:167], v[120:123]
	v_mfma_f32_16x16x32_bf16 v[124:127], v[216:219], v[208:211], v[124:127]
	v_mfma_f32_16x16x32_bf16 v[128:131], v[224:227], v[208:211], v[128:131]
	v_mfma_f32_16x16x32_bf16 v[100:103], v[220:223], v[152:155], v[100:103]
	v_mfma_f32_16x16x32_bf16 v[104:107], v[228:231], v[152:155], v[104:107]
	v_mfma_f32_16x16x32_bf16 v[108:111], v[220:223], v[160:163], v[108:111]
	v_mfma_f32_16x16x32_bf16 v[112:115], v[228:231], v[160:163], v[112:115]
	v_mfma_f32_16x16x32_bf16 v[116:119], v[220:223], v[168:171], v[116:119]
	v_mfma_f32_16x16x32_bf16 v[120:123], v[228:231], v[168:171], v[120:123]
	v_mfma_f32_16x16x32_bf16 v[124:127], v[220:223], v[212:215], v[124:127]
	v_mfma_f32_16x16x32_bf16 v[128:131], v[228:231], v[212:215], v[128:131]
	s_setprio 0
	s_add_i32 s27, s27, 2
	s_add_u32 s30, s30, 0x100
	s_addc_u32 s31, s31, 0
	s_add_u32 s2, s2, 0x100
	s_addc_u32 s3, s3, 0
	s_cmp_gt_u32 s27, 29
	s_barrier
	s_cbranch_scc0 .LBB0_903
	s_cmp_lg_u32 s70, 0
	s_cselect_b64 s[30:31], -1, 0
	v_lshl_add_u32 v144, s72, 8, v203
	v_lshl_or_b32 v146, s71, 8, v205
	s_and_b64 vcc, exec, s[30:31]
	v_ashrrev_i32_e32 v147, 31, v146
	v_or_b32_e32 v142, 16, v144
	v_or_b32_e32 v140, 32, v144
	v_or_b32_e32 v138, 48, v144
	v_add_u32_e32 v136, 0x80, v144
	v_add_u32_e32 v134, 0x90, v144
	v_add_u32_e32 v132, 0xa0, v144
	v_add_u32_e32 v2, 0xb0, v144
	s_cbranch_vccz .LBB0_910
	v_mov_b64_e32 v[150:151], s[92:93]
	v_mad_i64_i32 v[148:149], s[2:3], v144, s91, v[150:151]
	v_lshl_add_u64 v[158:159], v[148:149], 0, s[76:77]
	v_lshlrev_b64 v[148:149], 1, v[146:147]
	v_lshl_add_u64 v[152:153], v[158:159], 0, v[148:149]
	v_mov_b32_e32 v170, v152
	v_mov_b32_e32 v171, v153
	s_mov_b32 s74, 0x0
	s_mov_b32 s75, 0
	v_lshl_add_u64 v[208:209], v[170:171], 0, s[74:75]
	global_load_dwordx4 v[208:211], v[208:209], off
	s_mov_b32 s74, 0x100
	s_mov_b32 s75, 0
	v_lshl_add_u64 v[212:213], v[170:171], 0, s[74:75]
	global_load_dwordx4 v[212:215], v[212:213], off
	s_mov_b32 s74, 0x6a000
	s_mov_b32 s75, 0
	v_lshl_add_u64 v[216:217], v[170:171], 0, s[74:75]
	global_load_dwordx4 v[216:219], v[216:217], off
	s_mov_b32 s74, 0x6a100
	s_mov_b32 s75, 0
	v_lshl_add_u64 v[220:221], v[170:171], 0, s[74:75]
	global_load_dwordx4 v[220:223], v[220:221], off
	s_mov_b32 s74, 0xd4000
	s_mov_b32 s75, 0
	v_lshl_add_u64 v[224:225], v[170:171], 0, s[74:75]
	global_load_dwordx4 v[224:227], v[224:225], off
	s_mov_b32 s74, 0xd4100
	s_mov_b32 s75, 0
	v_lshl_add_u64 v[228:229], v[170:171], 0, s[74:75]
	global_load_dwordx4 v[228:231], v[228:229], off
	s_mov_b32 s74, 0x13e000
	s_mov_b32 s75, 0
	v_lshl_add_u64 v[232:233], v[170:171], 0, s[74:75]
	global_load_dwordx4 v[232:235], v[232:233], off
	s_mov_b32 s74, 0x13e100
	s_mov_b32 s75, 0
	v_lshl_add_u64 v[236:237], v[170:171], 0, s[74:75]
	global_load_dwordx4 v[236:239], v[236:237], off
	s_mov_b32 s74, 0x350000
	s_mov_b32 s75, 0
	v_lshl_add_u64 v[166:167], v[170:171], 0, s[74:75]
	global_load_dwordx4 v[166:169], v[166:167], off
	s_mov_b32 s74, 0x350100
	s_mov_b32 s75, 0
	v_lshl_add_u64 v[246:247], v[170:171], 0, s[74:75]
	global_load_dwordx4 v[246:249], v[246:247], off
	s_mov_b32 s74, 0x3ba000
	s_mov_b32 s75, 0
	v_lshl_add_u64 v[250:251], v[170:171], 0, s[74:75]
	global_load_dwordx4 v[250:253], v[250:251], off
	v_ashrrev_i32_e32 v145, 31, v144
	v_readlane_b32 s4, v244, 47
	v_lshlrev_b64 v[156:157], 12, v[144:145]
	v_readlane_b32 s8, v244, 51
	v_readlane_b32 s9, v244, 52
	v_ashrrev_i32_e32 v143, 31, v142
	v_lshlrev_b64 v[162:163], 12, v[142:143]
	v_lshl_add_u64 v[156:157], s[8:9], 0, v[156:157]
	v_lshl_add_u64 v[160:161], v[156:157], 0, v[148:149]
	v_ashrrev_i32_e32 v141, 31, v140
	v_ashrrev_i32_e32 v139, 31, v138
	v_ashrrev_i32_e32 v137, 31, v136
	v_ashrrev_i32_e32 v135, 31, v134
	v_ashrrev_i32_e32 v133, 31, v132
	v_readlane_b32 s5, v244, 48
	v_readlane_b32 s6, v244, 49
	v_readlane_b32 s7, v244, 50
	v_readlane_b32 s10, v244, 53
	v_readlane_b32 s11, v244, 54
	s_waitcnt vmcnt(10)
; __device__ __forceinline__ float bflo(unsigned w) { return __uint_as_float(w << 16); }
; __device__ __forceinline__ float bfhi(unsigned w) { return __uint_as_float(w & 0xffff0000u); }
; __device__ __forceinline__ unsigned pk2(float lo, float hi) { unsigned r; asm("v_cvt_pk_bf16_f32 %0, %1, %2" : "=v"(r) : "v"(lo), "v"(hi)); return r; }
;     __device__ __forceinline__ void operator()(const f32x4 (&acc)[2][2][4][2], const Unit& u, int wr, int wc, int fr, int fq) const {
;     ...
;             for (int m = 0; m < 4; ++m) { const int row = row0 + ai * HALF + m * 16;
; #pragma unroll
;                 for (int bj = 0; bj < 2; ++bj) { const int col = col0 + bj * HALF;
;                     const u32x4 gp = *(const u32x4*)(proj + (size_t)row * NPROJ + C_GP + col);
;                     const f32x4 v0 = acc[ai][bj][m][0], v1 = acc[ai][bj][m][1];
;                     u32x4 w; w.x = pk2(v0[0] * bflo(gp.x), v0[1] * bfhi(gp.x)); w.y = pk2(v0[2] * bflo(gp.y), v0[3] * bfhi(gp.y));
;                     w.z = pk2(v1[0] * bflo(gp.z), v1[1] * bfhi(gp.z)); w.w = pk2(v1[2] * bflo(gp.w), v1[3] * bfhi(gp.w));
;                     *(u32x4*)(merged + (size_t)row * DM + col) = w; } }
	v_mov_b32_e32 v152, v208
	v_mov_b32_e32 v153, v209
	v_mov_b32_e32 v154, v210
	v_mov_b32_e32 v155, v211
	s_mov_b32 s74, 0x3ba100
	s_mov_b32 s75, 0
	v_lshl_add_u64 v[208:209], v[170:171], 0, s[74:75]
	global_load_dwordx4 v[208:211], v[208:209], off
	v_lshlrev_b32_e32 v0, 16, v152
	v_and_b32_e32 v3, 0xffff0000, v152
	v_mul_f32_e32 v0, v4, v0
	v_mul_f32_e32 v3, v5, v3
	v_cvt_pk_bf16_f32 v152, v0, v3
	v_lshlrev_b32_e32 v0, 16, v153
	v_and_b32_e32 v3, 0xffff0000, v153
	v_mul_f32_e32 v0, v6, v0
	v_mul_f32_e32 v3, v7, v3
	v_cvt_pk_bf16_f32 v153, v0, v3
	v_lshlrev_b32_e32 v0, 16, v154
	v_and_b32_e32 v3, 0xffff0000, v154
	v_mul_f32_e32 v0, v8, v0
	v_mul_f32_e32 v3, v9, v3
	v_cvt_pk_bf16_f32 v154, v0, v3
	v_lshlrev_b32_e32 v0, 16, v155
	v_and_b32_e32 v3, 0xffff0000, v155
	v_mul_f32_e32 v0, v10, v0
	v_mul_f32_e32 v3, v11, v3
	v_cvt_pk_bf16_f32 v155, v0, v3
	global_store_dwordx4 v[160:161], v[152:155], off
	s_nop 1
	v_or_b32_e32 v152, 0x80, v146
	v_ashrrev_i32_e32 v153, 31, v152
	v_lshlrev_b64 v[152:153], 1, v[152:153]
	v_lshl_add_u64 v[154:155], v[158:159], 0, v[152:153]
	s_waitcnt vmcnt(11)
	v_mov_b32_e32 v154, v212
	v_mov_b32_e32 v155, v213
	v_mov_b32_e32 v156, v214
	v_mov_b32_e32 v157, v215
	s_mov_b32 s74, 0x424000
	s_mov_b32 s75, 0
	v_lshl_add_u64 v[212:213], v[170:171], 0, s[74:75]
	global_load_dwordx4 v[212:215], v[212:213], off
	v_lshlrev_b32_e32 v0, 16, v154
	v_and_b32_e32 v3, 0xffff0000, v154
	v_mul_f32_e32 v0, v36, v0
	v_mul_f32_e32 v3, v37, v3
	v_cvt_pk_bf16_f32 v154, v0, v3
	v_lshlrev_b32_e32 v0, 16, v155
	v_and_b32_e32 v3, 0xffff0000, v155
	v_mul_f32_e32 v0, v38, v0
	v_mul_f32_e32 v3, v39, v3
	v_cvt_pk_bf16_f32 v155, v0, v3
	v_lshlrev_b32_e32 v0, 16, v156
	v_and_b32_e32 v3, 0xffff0000, v156
	v_mul_f32_e32 v0, v40, v0
	v_mul_f32_e32 v3, v41, v3
	v_cvt_pk_bf16_f32 v156, v0, v3
	v_lshlrev_b32_e32 v0, 16, v157
	v_and_b32_e32 v3, 0xffff0000, v157
	v_mul_f32_e32 v0, v42, v0
	v_mul_f32_e32 v3, v43, v3
	v_cvt_pk_bf16_f32 v157, v0, v3
	global_store_dwordx4 v[160:161], v[154:157], off offset:256
	s_nop 1
	v_mad_i64_i32 v[154:155], s[2:3], v142, s91, v[150:151]
	v_lshl_add_u64 v[164:165], v[154:155], 0, s[76:77]
	v_lshl_add_u64 v[154:155], v[164:165], 0, v[148:149]
	s_waitcnt vmcnt(12)
	v_mov_b32_e32 v154, v216
	v_mov_b32_e32 v155, v217
	v_mov_b32_e32 v156, v218
	v_mov_b32_e32 v157, v219
	s_mov_b32 s74, 0x424100
	s_mov_b32 s75, 0
	v_lshl_add_u64 v[216:217], v[170:171], 0, s[74:75]
	global_load_dwordx4 v[216:219], v[216:217], off
	v_lshlrev_b32_e32 v0, 16, v154
	v_and_b32_e32 v3, 0xffff0000, v154
	v_mul_f32_e32 v0, v12, v0
	v_mul_f32_e32 v3, v13, v3
	v_cvt_pk_bf16_f32 v158, v0, v3
	v_lshlrev_b32_e32 v0, 16, v155
	v_and_b32_e32 v3, 0xffff0000, v155
	v_mul_f32_e32 v0, v14, v0
	v_mul_f32_e32 v3, v15, v3
	v_cvt_pk_bf16_f32 v159, v0, v3
	v_lshlrev_b32_e32 v0, 16, v156
	v_and_b32_e32 v3, 0xffff0000, v156
	v_mul_f32_e32 v0, v16, v0
	v_mul_f32_e32 v3, v17, v3
	v_lshl_add_u64 v[154:155], s[8:9], 0, v[162:163]
	v_cvt_pk_bf16_f32 v160, v0, v3
	v_lshlrev_b32_e32 v0, 16, v157
	v_and_b32_e32 v3, 0xffff0000, v157
	v_lshl_add_u64 v[154:155], v[154:155], 0, v[148:149]
	v_lshl_add_u64 v[156:157], v[164:165], 0, v[152:153]
	v_mul_f32_e32 v0, v18, v0
	v_mul_f32_e32 v3, v19, v3
	v_cvt_pk_bf16_f32 v161, v0, v3
	global_store_dwordx4 v[154:155], v[158:161], off
	v_lshlrev_b64 v[162:163], 12, v[140:141]
	s_waitcnt vmcnt(13)
	v_mov_b32_e32 v156, v220
	v_mov_b32_e32 v157, v221
	v_mov_b32_e32 v158, v222
	v_mov_b32_e32 v159, v223
	s_mov_b32 s74, 0x48e000
	s_mov_b32 s75, 0
	v_lshl_add_u64 v[220:221], v[170:171], 0, s[74:75]
	global_load_dwordx4 v[220:223], v[220:221], off
	v_lshlrev_b32_e32 v0, 16, v156
	v_and_b32_e32 v3, 0xffff0000, v156
	v_mul_f32_e32 v0, v44, v0
	v_mul_f32_e32 v3, v45, v3
	v_cvt_pk_bf16_f32 v156, v0, v3
	v_lshlrev_b32_e32 v0, 16, v157
	v_and_b32_e32 v3, 0xffff0000, v157
	v_mul_f32_e32 v0, v46, v0
	v_mul_f32_e32 v3, v47, v3
	v_cvt_pk_bf16_f32 v157, v0, v3
	v_lshlrev_b32_e32 v0, 16, v158
	v_and_b32_e32 v3, 0xffff0000, v158
	v_mul_f32_e32 v0, v48, v0
	v_mul_f32_e32 v3, v49, v3
	v_cvt_pk_bf16_f32 v158, v0, v3
	v_lshlrev_b32_e32 v0, 16, v159
	v_and_b32_e32 v3, 0xffff0000, v159
	v_mul_f32_e32 v0, v50, v0
	v_mul_f32_e32 v3, v51, v3
	v_cvt_pk_bf16_f32 v159, v0, v3
	global_store_dwordx4 v[154:155], v[156:159], off offset:256
	v_mad_i64_i32 v[154:155], s[2:3], v140, s91, v[150:151]
	v_lshl_add_u64 v[164:165], v[154:155], 0, s[76:77]
	v_lshl_add_u64 v[154:155], v[164:165], 0, v[148:149]
	s_waitcnt vmcnt(14)
	v_mov_b32_e32 v154, v224
	v_mov_b32_e32 v155, v225
	v_mov_b32_e32 v156, v226
	v_mov_b32_e32 v157, v227
	s_mov_b32 s74, 0x48e100
	s_mov_b32 s75, 0
	v_lshl_add_u64 v[224:225], v[170:171], 0, s[74:75]
	global_load_dwordx4 v[224:227], v[224:225], off
	v_lshlrev_b32_e32 v0, 16, v154
	v_and_b32_e32 v3, 0xffff0000, v154
	v_mul_f32_e32 v0, v20, v0
	v_mul_f32_e32 v3, v21, v3
	v_cvt_pk_bf16_f32 v158, v0, v3
	v_lshlrev_b32_e32 v0, 16, v155
	v_and_b32_e32 v3, 0xffff0000, v155
	v_mul_f32_e32 v0, v22, v0
	v_mul_f32_e32 v3, v23, v3
	v_cvt_pk_bf16_f32 v159, v0, v3
	v_lshlrev_b32_e32 v0, 16, v156
	v_and_b32_e32 v3, 0xffff0000, v156
	v_mul_f32_e32 v0, v24, v0
	v_mul_f32_e32 v3, v25, v3
	v_lshl_add_u64 v[154:155], s[8:9], 0, v[162:163]
	v_cvt_pk_bf16_f32 v160, v0, v3
	v_lshlrev_b32_e32 v0, 16, v157
	v_and_b32_e32 v3, 0xffff0000, v157
	v_lshl_add_u64 v[154:155], v[154:155], 0, v[148:149]
	v_lshl_add_u64 v[156:157], v[164:165], 0, v[152:153]
	v_mul_f32_e32 v0, v26, v0
	v_mul_f32_e32 v3, v27, v3
	v_cvt_pk_bf16_f32 v161, v0, v3
	global_store_dwordx4 v[154:155], v[158:161], off
	v_lshlrev_b64 v[162:163], 12, v[138:139]
	s_waitcnt vmcnt(15)
; __device__ __forceinline__ float bflo(unsigned w) { return __uint_as_float(w << 16); }
; __device__ __forceinline__ float bfhi(unsigned w) { return __uint_as_float(w & 0xffff0000u); }
; __device__ __forceinline__ unsigned pk2(float lo, float hi) { unsigned r; asm("v_cvt_pk_bf16_f32 %0, %1, %2" : "=v"(r) : "v"(lo), "v"(hi)); return r; }
;     __device__ __forceinline__ void operator()(const f32x4 (&acc)[2][2][4][2], const Unit& u, int wr, int wc, int fr, int fq) const {
;     ...
;             for (int m = 0; m < 4; ++m) { const int row = row0 + ai * HALF + m * 16;
; #pragma unroll
;                 for (int bj = 0; bj < 2; ++bj) { const int col = col0 + bj * HALF;
;                     const u32x4 gp = *(const u32x4*)(proj + (size_t)row * NPROJ + C_GP + col);
;                     const f32x4 v0 = acc[ai][bj][m][0], v1 = acc[ai][bj][m][1];
;                     u32x4 w; w.x = pk2(v0[0] * bflo(gp.x), v0[1] * bfhi(gp.x)); w.y = pk2(v0[2] * bflo(gp.y), v0[3] * bfhi(gp.y));
;                     w.z = pk2(v1[0] * bflo(gp.z), v1[1] * bfhi(gp.z)); w.w = pk2(v1[2] * bflo(gp.w), v1[3] * bfhi(gp.w));
;                     *(u32x4*)(merged + (size_t)row * DM + col) = w; } }
	v_mov_b32_e32 v156, v228
	v_mov_b32_e32 v157, v229
	v_mov_b32_e32 v158, v230
	v_mov_b32_e32 v159, v231
	v_lshlrev_b32_e32 v0, 16, v156
	v_and_b32_e32 v3, 0xffff0000, v156
	v_mul_f32_e32 v0, v52, v0
	v_mul_f32_e32 v3, v53, v3
	v_cvt_pk_bf16_f32 v156, v0, v3
	v_lshlrev_b32_e32 v0, 16, v157
	v_and_b32_e32 v3, 0xffff0000, v157
	v_mul_f32_e32 v0, v54, v0
	v_mul_f32_e32 v3, v55, v3
	v_cvt_pk_bf16_f32 v157, v0, v3
	v_lshlrev_b32_e32 v0, 16, v158
	v_and_b32_e32 v3, 0xffff0000, v158
	v_mul_f32_e32 v0, v56, v0
	v_mul_f32_e32 v3, v57, v3
	v_cvt_pk_bf16_f32 v158, v0, v3
	v_lshlrev_b32_e32 v0, 16, v159
	v_and_b32_e32 v3, 0xffff0000, v159
	v_mul_f32_e32 v0, v58, v0
	v_mul_f32_e32 v3, v59, v3
	v_cvt_pk_bf16_f32 v159, v0, v3
	global_store_dwordx4 v[154:155], v[156:159], off offset:256
	v_mad_i64_i32 v[154:155], s[2:3], v138, s91, v[150:151]
	v_lshl_add_u64 v[164:165], v[154:155], 0, s[76:77]
	v_lshl_add_u64 v[154:155], v[164:165], 0, v[148:149]
	s_waitcnt vmcnt(15)
	v_mov_b32_e32 v154, v232
	v_mov_b32_e32 v155, v233
	v_mov_b32_e32 v156, v234
	v_mov_b32_e32 v157, v235
	v_lshlrev_b32_e32 v0, 16, v154
	v_and_b32_e32 v3, 0xffff0000, v154
	v_mul_f32_e32 v0, v28, v0
	v_mul_f32_e32 v3, v29, v3
	v_cvt_pk_bf16_f32 v158, v0, v3
	v_lshlrev_b32_e32 v0, 16, v155
	v_and_b32_e32 v3, 0xffff0000, v155
	v_mul_f32_e32 v0, v30, v0
	v_mul_f32_e32 v3, v31, v3
	v_cvt_pk_bf16_f32 v159, v0, v3
	v_lshlrev_b32_e32 v0, 16, v156
	v_and_b32_e32 v3, 0xffff0000, v156
	v_mul_f32_e32 v0, v32, v0
	v_mul_f32_e32 v3, v33, v3
	v_lshl_add_u64 v[154:155], s[8:9], 0, v[162:163]
	v_cvt_pk_bf16_f32 v160, v0, v3
	v_lshlrev_b32_e32 v0, 16, v157
	v_and_b32_e32 v3, 0xffff0000, v157
	v_lshl_add_u64 v[154:155], v[154:155], 0, v[148:149]
	v_lshl_add_u64 v[156:157], v[164:165], 0, v[152:153]
	v_mul_f32_e32 v0, v34, v0
	v_mul_f32_e32 v3, v35, v3
	v_cvt_pk_bf16_f32 v161, v0, v3
	global_store_dwordx4 v[154:155], v[158:161], off
	v_lshlrev_b64 v[162:163], 12, v[136:137]
	s_waitcnt vmcnt(15)
	v_mov_b32_e32 v156, v236
	v_mov_b32_e32 v157, v237
	v_mov_b32_e32 v158, v238
	v_mov_b32_e32 v159, v239
	v_lshlrev_b32_e32 v0, 16, v156
	v_and_b32_e32 v3, 0xffff0000, v156
	v_mul_f32_e32 v0, v60, v0
	v_mul_f32_e32 v3, v61, v3
	v_cvt_pk_bf16_f32 v156, v0, v3
	v_lshlrev_b32_e32 v0, 16, v157
	v_and_b32_e32 v3, 0xffff0000, v157
	v_mul_f32_e32 v0, v62, v0
	v_mul_f32_e32 v3, v63, v3
	v_cvt_pk_bf16_f32 v157, v0, v3
	v_lshlrev_b32_e32 v0, 16, v158
	v_and_b32_e32 v3, 0xffff0000, v158
	v_mul_f32_e32 v0, v64, v0
	v_mul_f32_e32 v3, v65, v3
	v_cvt_pk_bf16_f32 v158, v0, v3
	v_lshlrev_b32_e32 v0, 16, v159
	v_and_b32_e32 v3, 0xffff0000, v159
	v_mul_f32_e32 v0, v66, v0
	v_mul_f32_e32 v3, v67, v3
	v_cvt_pk_bf16_f32 v159, v0, v3
	global_store_dwordx4 v[154:155], v[156:159], off offset:256
	v_mad_i64_i32 v[154:155], s[2:3], v136, s91, v[150:151]
	v_lshl_add_u64 v[164:165], v[154:155], 0, s[76:77]
	v_lshl_add_u64 v[154:155], v[164:165], 0, v[148:149]
	s_waitcnt vmcnt(15)
	v_mov_b32_e32 v154, v166
	v_mov_b32_e32 v155, v167
	v_mov_b32_e32 v156, v168
	v_mov_b32_e32 v157, v169
	v_lshlrev_b32_e32 v0, 16, v154
	v_and_b32_e32 v3, 0xffff0000, v154
	v_mul_f32_e32 v0, v68, v0
	v_mul_f32_e32 v3, v69, v3
	v_cvt_pk_bf16_f32 v158, v0, v3
	v_lshlrev_b32_e32 v0, 16, v155
	v_and_b32_e32 v3, 0xffff0000, v155
	v_mul_f32_e32 v0, v70, v0
	v_mul_f32_e32 v3, v71, v3
	v_cvt_pk_bf16_f32 v159, v0, v3
	v_lshlrev_b32_e32 v0, 16, v156
	v_and_b32_e32 v3, 0xffff0000, v156
	v_mul_f32_e32 v0, v72, v0
	v_mul_f32_e32 v3, v73, v3
	v_lshl_add_u64 v[154:155], s[8:9], 0, v[162:163]
	v_cvt_pk_bf16_f32 v160, v0, v3
	v_lshlrev_b32_e32 v0, 16, v157
	v_and_b32_e32 v3, 0xffff0000, v157
	v_lshl_add_u64 v[154:155], v[154:155], 0, v[148:149]
	v_lshl_add_u64 v[156:157], v[164:165], 0, v[152:153]
	v_mul_f32_e32 v0, v74, v0
	v_mul_f32_e32 v3, v75, v3
	v_cvt_pk_bf16_f32 v161, v0, v3
	global_store_dwordx4 v[154:155], v[158:161], off
	v_lshlrev_b64 v[162:163], 12, v[134:135]
	s_waitcnt vmcnt(15)
	v_mov_b32_e32 v156, v246
	v_mov_b32_e32 v157, v247
	v_mov_b32_e32 v158, v248
	v_mov_b32_e32 v159, v249
	v_lshlrev_b32_e32 v0, 16, v156
	v_and_b32_e32 v3, 0xffff0000, v156
	v_mul_f32_e32 v0, v100, v0
	v_mul_f32_e32 v3, v101, v3
	v_cvt_pk_bf16_f32 v156, v0, v3
	v_lshlrev_b32_e32 v0, 16, v157
	v_and_b32_e32 v3, 0xffff0000, v157
	v_mul_f32_e32 v0, v102, v0
	v_mul_f32_e32 v3, v103, v3
	v_cvt_pk_bf16_f32 v157, v0, v3
	v_lshlrev_b32_e32 v0, 16, v158
	v_and_b32_e32 v3, 0xffff0000, v158
	v_mul_f32_e32 v0, v104, v0
	v_mul_f32_e32 v3, v105, v3
	v_cvt_pk_bf16_f32 v158, v0, v3
	v_lshlrev_b32_e32 v0, 16, v159
	v_and_b32_e32 v3, 0xffff0000, v159
	v_mul_f32_e32 v0, v106, v0
	v_mul_f32_e32 v3, v107, v3
	v_cvt_pk_bf16_f32 v159, v0, v3
	global_store_dwordx4 v[154:155], v[156:159], off offset:256
	v_mad_i64_i32 v[154:155], s[2:3], v134, s91, v[150:151]
	v_lshl_add_u64 v[164:165], v[154:155], 0, s[76:77]
	v_lshl_add_u64 v[154:155], v[164:165], 0, v[148:149]
	s_waitcnt vmcnt(15)
; __device__ __forceinline__ float bflo(unsigned w) { return __uint_as_float(w << 16); }
; __device__ __forceinline__ float bfhi(unsigned w) { return __uint_as_float(w & 0xffff0000u); }
; __device__ __forceinline__ unsigned pk2(float lo, float hi) { unsigned r; asm("v_cvt_pk_bf16_f32 %0, %1, %2" : "=v"(r) : "v"(lo), "v"(hi)); return r; }
;     __device__ __forceinline__ void operator()(const f32x4 (&acc)[2][2][4][2], const Unit& u, int wr, int wc, int fr, int fq) const {
;     ...
;             for (int m = 0; m < 4; ++m) { const int row = row0 + ai * HALF + m * 16;
; #pragma unroll
;                 for (int bj = 0; bj < 2; ++bj) { const int col = col0 + bj * HALF;
;                     const u32x4 gp = *(const u32x4*)(proj + (size_t)row * NPROJ + C_GP + col);
;                     const f32x4 v0 = acc[ai][bj][m][0], v1 = acc[ai][bj][m][1];
;                     u32x4 w; w.x = pk2(v0[0] * bflo(gp.x), v0[1] * bfhi(gp.x)); w.y = pk2(v0[2] * bflo(gp.y), v0[3] * bfhi(gp.y));
;                     w.z = pk2(v1[0] * bflo(gp.z), v1[1] * bfhi(gp.z)); w.w = pk2(v1[2] * bflo(gp.w), v1[3] * bfhi(gp.w));
;                     *(u32x4*)(merged + (size_t)row * DM + col) = w; } }
	v_mov_b32_e32 v154, v250
	v_mov_b32_e32 v155, v251
	v_mov_b32_e32 v156, v252
	v_mov_b32_e32 v157, v253
	v_lshlrev_b32_e32 v0, 16, v154
	v_and_b32_e32 v3, 0xffff0000, v154
	v_mul_f32_e32 v0, v76, v0
	v_mul_f32_e32 v3, v77, v3
	v_cvt_pk_bf16_f32 v158, v0, v3
	v_lshlrev_b32_e32 v0, 16, v155
	v_and_b32_e32 v3, 0xffff0000, v155
	v_mul_f32_e32 v0, v78, v0
	v_mul_f32_e32 v3, v79, v3
	v_cvt_pk_bf16_f32 v159, v0, v3
	v_lshlrev_b32_e32 v0, 16, v156
	v_and_b32_e32 v3, 0xffff0000, v156
	v_mul_f32_e32 v0, v80, v0
	v_mul_f32_e32 v3, v81, v3
	v_lshl_add_u64 v[154:155], s[8:9], 0, v[162:163]
	v_cvt_pk_bf16_f32 v160, v0, v3
	v_lshlrev_b32_e32 v0, 16, v157
	v_and_b32_e32 v3, 0xffff0000, v157
	v_lshl_add_u64 v[154:155], v[154:155], 0, v[148:149]
	v_lshl_add_u64 v[156:157], v[164:165], 0, v[152:153]
	v_mul_f32_e32 v0, v82, v0
	v_mul_f32_e32 v3, v83, v3
	v_cvt_pk_bf16_f32 v161, v0, v3
	global_store_dwordx4 v[154:155], v[158:161], off
	v_lshlrev_b64 v[162:163], 12, v[132:133]
	s_waitcnt vmcnt(15)
	v_mov_b32_e32 v156, v208
	v_mov_b32_e32 v157, v209
	v_mov_b32_e32 v158, v210
	v_mov_b32_e32 v159, v211
	v_lshlrev_b32_e32 v0, 16, v156
	v_and_b32_e32 v3, 0xffff0000, v156
	v_mul_f32_e32 v0, v108, v0
	v_mul_f32_e32 v3, v109, v3
	v_cvt_pk_bf16_f32 v156, v0, v3
	v_lshlrev_b32_e32 v0, 16, v157
	v_and_b32_e32 v3, 0xffff0000, v157
	v_mul_f32_e32 v0, v110, v0
	v_mul_f32_e32 v3, v111, v3
	v_cvt_pk_bf16_f32 v157, v0, v3
	v_lshlrev_b32_e32 v0, 16, v158
	v_and_b32_e32 v3, 0xffff0000, v158
	v_mul_f32_e32 v0, v112, v0
	v_mul_f32_e32 v3, v113, v3
	v_cvt_pk_bf16_f32 v158, v0, v3
	v_lshlrev_b32_e32 v0, 16, v159
	v_and_b32_e32 v3, 0xffff0000, v159
	v_mul_f32_e32 v0, v114, v0
	v_mul_f32_e32 v3, v115, v3
	v_cvt_pk_bf16_f32 v159, v0, v3
	global_store_dwordx4 v[154:155], v[156:159], off offset:256
	v_mad_i64_i32 v[154:155], s[2:3], v132, s91, v[150:151]
	v_lshl_add_u64 v[164:165], v[154:155], 0, s[76:77]
	v_lshl_add_u64 v[154:155], v[164:165], 0, v[148:149]
	v_mad_i64_i32 v[150:151], s[2:3], v2, s91, v[150:151]
	v_lshl_add_u64 v[150:151], v[150:151], 0, s[76:77]
	s_waitcnt vmcnt(14)
	v_mov_b32_e32 v154, v212
	v_mov_b32_e32 v155, v213
	v_mov_b32_e32 v156, v214
	v_mov_b32_e32 v157, v215
	v_lshlrev_b32_e32 v0, 16, v154
	v_and_b32_e32 v3, 0xffff0000, v154
	v_mul_f32_e32 v0, v84, v0
	v_mul_f32_e32 v3, v85, v3
	v_cvt_pk_bf16_f32 v158, v0, v3
	v_lshlrev_b32_e32 v0, 16, v155
	v_and_b32_e32 v3, 0xffff0000, v155
	v_mul_f32_e32 v0, v86, v0
	v_mul_f32_e32 v3, v87, v3
	v_cvt_pk_bf16_f32 v159, v0, v3
	v_lshlrev_b32_e32 v0, 16, v156
	v_and_b32_e32 v3, 0xffff0000, v156
	v_mul_f32_e32 v0, v88, v0
	v_mul_f32_e32 v3, v89, v3
	v_lshl_add_u64 v[154:155], s[8:9], 0, v[162:163]
	v_cvt_pk_bf16_f32 v160, v0, v3
	v_lshlrev_b32_e32 v0, 16, v157
	v_and_b32_e32 v3, 0xffff0000, v157
	v_lshl_add_u64 v[154:155], v[154:155], 0, v[148:149]
	v_lshl_add_u64 v[156:157], v[164:165], 0, v[152:153]
	v_mul_f32_e32 v0, v90, v0
	v_mul_f32_e32 v3, v91, v3
	v_cvt_pk_bf16_f32 v161, v0, v3
	global_store_dwordx4 v[154:155], v[158:161], off
	s_waitcnt vmcnt(13)
	v_mov_b32_e32 v156, v216
	v_mov_b32_e32 v157, v217
	v_mov_b32_e32 v158, v218
	v_mov_b32_e32 v159, v219
	v_lshlrev_b32_e32 v0, 16, v156
	v_and_b32_e32 v3, 0xffff0000, v156
	v_mul_f32_e32 v0, v116, v0
	v_mul_f32_e32 v3, v117, v3
	v_cvt_pk_bf16_f32 v156, v0, v3
	v_lshlrev_b32_e32 v0, 16, v157
	v_and_b32_e32 v3, 0xffff0000, v157
	v_mul_f32_e32 v0, v118, v0
	v_mul_f32_e32 v3, v119, v3
	v_cvt_pk_bf16_f32 v157, v0, v3
	v_lshlrev_b32_e32 v0, 16, v158
	v_and_b32_e32 v3, 0xffff0000, v158
	v_mul_f32_e32 v0, v120, v0
	v_mul_f32_e32 v3, v121, v3
	v_cvt_pk_bf16_f32 v158, v0, v3
	v_lshlrev_b32_e32 v0, 16, v159
	v_and_b32_e32 v3, 0xffff0000, v159
	v_mul_f32_e32 v0, v122, v0
	v_mul_f32_e32 v3, v123, v3
	v_cvt_pk_bf16_f32 v159, v0, v3
	global_store_dwordx4 v[154:155], v[156:159], off offset:256
	v_lshl_add_u64 v[154:155], v[150:151], 0, v[148:149]
	v_lshl_add_u64 v[150:151], v[150:151], 0, v[152:153]
	v_ashrrev_i32_e32 v3, 31, v2
	v_lshlrev_b64 v[158:159], 12, v[2:3]
	v_lshl_add_u64 v[158:159], s[8:9], 0, v[158:159]
	v_lshl_add_u64 v[148:149], v[158:159], 0, v[148:149]
	s_waitcnt vmcnt(10)
	v_mov_b32_e32 v154, v220
	v_mov_b32_e32 v155, v221
	v_mov_b32_e32 v156, v222
	v_mov_b32_e32 v157, v223
	v_mov_b32_e32 v150, v224
	v_mov_b32_e32 v151, v225
	v_mov_b32_e32 v152, v226
	v_mov_b32_e32 v153, v227
	v_lshlrev_b32_e32 v0, 16, v154
	v_and_b32_e32 v3, 0xffff0000, v154
	v_mul_f32_e32 v0, v92, v0
	v_mul_f32_e32 v3, v93, v3
	v_cvt_pk_bf16_f32 v154, v0, v3
	v_lshlrev_b32_e32 v0, 16, v155
	v_and_b32_e32 v3, 0xffff0000, v155
	v_mul_f32_e32 v0, v94, v0
	v_mul_f32_e32 v3, v95, v3
	v_cvt_pk_bf16_f32 v155, v0, v3
	v_lshlrev_b32_e32 v0, 16, v156
	v_and_b32_e32 v3, 0xffff0000, v156
	v_mul_f32_e32 v0, v96, v0
	v_mul_f32_e32 v3, v97, v3
	v_cvt_pk_bf16_f32 v156, v0, v3
	v_lshlrev_b32_e32 v0, 16, v157
	v_and_b32_e32 v3, 0xffff0000, v157
	v_mul_f32_e32 v0, v98, v0
	v_mul_f32_e32 v3, v99, v3
	v_cvt_pk_bf16_f32 v157, v0, v3
	v_lshlrev_b32_e32 v0, 16, v150
	v_and_b32_e32 v3, 0xffff0000, v150
	v_mul_f32_e32 v0, v124, v0
	v_mul_f32_e32 v3, v125, v3
	v_cvt_pk_bf16_f32 v150, v0, v3
	v_lshlrev_b32_e32 v0, 16, v151
	v_and_b32_e32 v3, 0xffff0000, v151
	v_mul_f32_e32 v0, v126, v0
	v_mul_f32_e32 v3, v127, v3
	v_cvt_pk_bf16_f32 v151, v0, v3
	v_lshlrev_b32_e32 v0, 16, v152
	v_and_b32_e32 v3, 0xffff0000, v152
	v_mul_f32_e32 v0, v128, v0
	v_mul_f32_e32 v3, v129, v3
	v_cvt_pk_bf16_f32 v152, v0, v3
	v_lshlrev_b32_e32 v0, 16, v153
	v_and_b32_e32 v3, 0xffff0000, v153
	global_store_dwordx4 v[148:149], v[154:157], off
	v_mul_f32_e32 v0, v130, v0
	v_mul_f32_e32 v3, v131, v3
	v_cvt_pk_bf16_f32 v153, v0, v3
	global_store_dwordx4 v[148:149], v[150:153], off offset:256
	s_cbranch_execnz .LBB0_907
